# chained MFMA order + residual GEMM phases align the wave halves around each epilogue
# speedup vs baseline: 1.0096x; 1.0096x over previous
; #define PG8_BAR __builtin_amdgcn_s_barrier()
;     __host__ __device__ bool next(int i, Unit& u) const {
;         const long L = (long)i * G + c; if (L >= nwg) return false;
;         int wgid = (int)L; { const int q = nwg / NXCD, r = nwg % NXCD, xcd = wgid % NXCD, off = wgid / NXCD; wgid = (xcd < r ? xcd * (q + 1) : r * (q + 1) + (xcd - r) * q) + off; }
;         const int nig = WGM * nN, gid = wgid / nig, fm = gid * WGM, gsz = (nM - fm) < WGM ? (nM - fm) : WGM;
;         u.pm = fm + ((wgid % nig) % gsz); u.pn = (wgid % nig) / gsz; return true;
; template <class Epi, class Sched, bool ALIGN_EPI = false, bool SP2 = false>
; __device__ __forceinline__ void gemm_phase(PG8_LAS unsigned char* lds, const Gemm g, const Sched& S, const Epi& E) {
;     ...
;         cur = nxt; cA = nA; cB = nB; ++ui;
;         if constexpr (ALIGN_EPI) { if (wr == 1) PG8_BAR; }
.LBB0_547:
	s_or_b64 exec, exec, s[4:5]
	s_and_b64 vcc, exec, s[2:3]
	s_mov_b32 s33, s48
	s_mov_b32 s29, s50
	s_mov_b64 s[6:7], s[54:55]
	s_mov_b64 s[4:5], s[52:53]
	s_cbranch_vccnz .LBB0_572
	s_cmp_eq_u32 s98, 0
	s_cbranch_scc1 .Lal_0
	s_barrier
.Lal_0:
.LBB0_548:
	s_add_i32 s28, s28, 1
	s_mul_i32 s2, s28, s77
	s_mul_hi_u32 s3, s28, s76
	s_add_i32 s3, s3, s2
	s_mul_i32 s2, s28, s76
	s_add_u32 s8, s2, s73
	s_addc_u32 s9, s3, s72
	v_cmp_gt_i64_e64 s[2:3], s[8:9], v[170:171]
	s_and_b64 vcc, exec, s[2:3]
	s_cbranch_vccnz .LBB0_554
	s_ashr_i32 s10, s8, 31
	s_lshr_b32 s10, s10, 29
	s_add_i32 s12, s8, s10
	s_and_b32 s10, s12, -8
	s_sub_i32 s13, s8, s10
	s_cmp_gt_i32 s13, -1
	s_mov_b64 s[10:11], -1
	s_cbranch_scc0 .LBB0_551
	s_lshl_b32 s34, s13, 6
	s_mov_b64 s[10:11], 0

; #define PG8_STAGE(bufoff, gbase, voff) do { const char* gb_ = (const char*)(gbase); asm volatile("" : "+s"(gb_)); _Pragma("unroll") for (int _i = 0; _i < 2; ++_i) { unsigned vo_ = (voff)[_i]; asm volatile("" : "+v"(vo_));        \
;         __builtin_amdgcn_global_load_lds((const unsigned*)(gb_ + vo_), (PG8_LAS unsigned*)(lds + (bufoff) + ldsw + _i * 8192), 16, 0, 0); } } while (0)
; #define PG8_LDA(dst, b, h) do { _Pragma("unroll") for (int m = 0; m < 4; ++m) _Pragma("unroll") for (int k = 0; k < 2; ++k) dst[m][k] = *(const PG8_LAS bf16x8*)(lds + PG8_SA(b, h) + aoff + m * 2048 + k * 1024); } while (0)
; #define PG8_LDB(dst, b, h) do { _Pragma("unroll") for (int n = 0; n < 2; ++n) _Pragma("unroll") for (int k = 0; k < 2; ++k) dst[n][k] = *(const PG8_LAS bf16x8*)(lds + PG8_SB(b, h) + boff + n * 2048 + k * 1024); } while (0)
; #define PG8_MMA(ai, bj, At, Bt) do { __builtin_amdgcn_s_setprio(1); _Pragma("unroll") for (int m = 0; m < 4; ++m) _Pragma("unroll") for (int n = 0; n < 2; ++n) _Pragma("unroll") for (int k = 0; k < 2; ++k) \
;         acc[ai][bj][m][n] = __builtin_amdgcn_mfma_f32_16x16x32_bf16(Bt[n][k], At[m][k], acc[ai][bj][m][n], 0, 0, 0); __builtin_amdgcn_s_setprio(0); } while (0)
; #define PG8_WAIT_V(n) asm volatile("s_waitcnt vmcnt(" #n ")" ::: "memory")
; template <class Epi, class Sched, bool ALIGN_EPI = false, bool SP2 = false>
; __device__ __forceinline__ void gemm_phase(PG8_LAS unsigned char* lds, const Gemm g, const Sched& S, const Epi& E) {
;     ...
;             const bool last = (t == nt - 2);
;             const char* a1 = cA + (size_t)(t + 1) * kstep;
;             const char* a2 = last ? nA : cA + (size_t)(t + 2) * kstep; const char* b2 = last ? nB : cB + (size_t)(t + 2) * kstep;
;             const char* a3 = a2 + kstep; const char* b3 = b2 + kstep;
;             if (last && has_next) S.a_ready(nxt);
;             if constexpr (SP2) {
;             PG8_LDB(B0, 0, 0); PG8_LDB(B1, 0, 1); PG8_SCHED; PG8_LDA(At, 0, 0); PG8_STAGE(PG8_SA(1, 1), a1 + hstep, voffA);
;             PG8_WAIT_V(8); PG8_WAIT_L(0); PG8_BAR; PG8_MMA(0, 0, At, B0); PG8_MMA(0, 1, At, B1); PG8_BAR; PG8_SCHED;
;             PG8_LDA(At, 0, 1); PG8_STAGE(PG8_SB(0, 0), b2, voffB); PG8_STAGE(PG8_SB(0, 1), b2 + hstep, voffB); PG8_STAGE(PG8_SA(0, 0), a2, voffA);
;             PG8_WAIT_V(8); PG8_WAIT_L(0); PG8_BAR; PG8_MMA(1, 0, At, B0); PG8_MMA(1, 1, At, B1); PG8_BAR; PG8_SCHED;
.LBB0_555:
	s_add_u32 s6, s4, 0x100
	s_addc_u32 s7, s5, 0
	s_cmp_eq_u32 s51, 28
	s_cselect_b32 s12, s35, s6
	s_cselect_b32 s13, s34, s7
	s_cselect_b32 s10, s39, s40
	s_cselect_b32 s11, s38, s49
	s_add_u32 s8, s12, 0x80
	s_addc_u32 s9, s13, 0
	s_add_i32 s56, 0, 0x10000
	s_add_i32 s57, 0, 0x14000
	ds_read_b128 v[26:29], v244
	ds_read_b128 v[30:33], v244 offset:1024
	ds_read_b128 v[98:101], v244 offset:2048
	ds_read_b128 v[102:105], v244 offset:3072
	ds_read_b128 v[146:149], v244 offset:16384
	ds_read_b128 v[150:153], v244 offset:17408
	ds_read_b128 v[154:157], v244 offset:18432
	ds_read_b128 v[158:161], v244 offset:19456
	s_add_u32 s4, s4, 0x80080
	s_addc_u32 s5, s5, 0
	ds_read_b128 v[178:181], v210
	ds_read_b128 v[182:185], v210 offset:1024
	ds_read_b128 v[186:189], v210 offset:2048
	ds_read_b128 v[190:193], v210 offset:3072
	ds_read_b128 v[194:197], v210 offset:4096
	ds_read_b128 v[198:201], v210 offset:5120
	ds_read_b128 v[202:205], v210 offset:6144
	ds_read_b128 v[212:215], v210 offset:7168
	s_add_i32 m0, s18, 0xc000
	s_nop 0
	global_load_lds_dwordx4 v1, s[4:5]
	s_add_i32 m0, s18, 0xe000
	s_nop 0
	global_load_lds_dwordx4 v164, s[4:5]
	s_waitcnt vmcnt(8)
	s_waitcnt lgkmcnt(0)
	s_barrier
	s_setprio 1
	s_waitcnt lgkmcnt(0)
	v_mfma_f32_16x16x32_bf16 v[142:145], v[26:29], v[178:181], v[142:145]
	v_mfma_f32_16x16x32_bf16 v[142:145], v[30:33], v[182:185], v[142:145]
	v_mfma_f32_16x16x32_bf16 v[134:137], v[26:29], v[186:189], v[134:137]
	v_mfma_f32_16x16x32_bf16 v[134:137], v[30:33], v[190:193], v[134:137]
	v_mfma_f32_16x16x32_bf16 v[126:129], v[26:29], v[194:197], v[126:129]
	v_mfma_f32_16x16x32_bf16 v[126:129], v[30:33], v[198:201], v[126:129]
	v_mfma_f32_16x16x32_bf16 v[118:121], v[26:29], v[202:205], v[118:121]
	v_mfma_f32_16x16x32_bf16 v[118:121], v[30:33], v[212:215], v[118:121]
	v_mfma_f32_16x16x32_bf16 v[138:141], v[98:101], v[178:181], v[138:141]
	v_mfma_f32_16x16x32_bf16 v[138:141], v[102:105], v[182:185], v[138:141]
	v_mfma_f32_16x16x32_bf16 v[130:133], v[98:101], v[186:189], v[130:133]
	v_mfma_f32_16x16x32_bf16 v[130:133], v[102:105], v[190:193], v[130:133]
	v_mfma_f32_16x16x32_bf16 v[122:125], v[98:101], v[194:197], v[122:125]
	v_mfma_f32_16x16x32_bf16 v[122:125], v[102:105], v[198:201], v[122:125]
	v_mfma_f32_16x16x32_bf16 v[114:117], v[98:101], v[202:205], v[114:117]
	v_mfma_f32_16x16x32_bf16 v[114:117], v[102:105], v[212:215], v[114:117]
	s_setprio 0
	s_setprio 1
	v_mfma_f32_16x16x32_bf16 v[70:73], v[146:149], v[178:181], v[70:73]
	v_mfma_f32_16x16x32_bf16 v[70:73], v[150:153], v[182:185], v[70:73]
	v_mfma_f32_16x16x32_bf16 v[62:65], v[146:149], v[186:189], v[62:65]
	v_mfma_f32_16x16x32_bf16 v[62:65], v[150:153], v[190:193], v[62:65]
	v_mfma_f32_16x16x32_bf16 v[54:57], v[146:149], v[194:197], v[54:57]
	v_mfma_f32_16x16x32_bf16 v[54:57], v[150:153], v[198:201], v[54:57]
	v_mfma_f32_16x16x32_bf16 v[46:49], v[146:149], v[202:205], v[46:49]
	v_mfma_f32_16x16x32_bf16 v[46:49], v[150:153], v[212:215], v[46:49]
	v_mfma_f32_16x16x32_bf16 v[66:69], v[154:157], v[178:181], v[66:69]
	v_mfma_f32_16x16x32_bf16 v[66:69], v[158:161], v[182:185], v[66:69]
	v_mfma_f32_16x16x32_bf16 v[58:61], v[154:157], v[186:189], v[58:61]
	v_mfma_f32_16x16x32_bf16 v[58:61], v[158:161], v[190:193], v[58:61]
	v_mfma_f32_16x16x32_bf16 v[50:53], v[154:157], v[194:197], v[50:53]
	v_mfma_f32_16x16x32_bf16 v[50:53], v[158:161], v[198:201], v[50:53]
	v_mfma_f32_16x16x32_bf16 v[42:45], v[154:157], v[202:205], v[42:45]
	v_mfma_f32_16x16x32_bf16 v[42:45], v[158:161], v[212:215], v[42:45]
	s_setprio 0
	s_barrier
	s_mov_b64 s[4:5], s[10:11]
	s_add_i32 s56, s56, s17
	ds_read_b128 v[178:181], v210 offset:16384
	ds_read_b128 v[182:185], v210 offset:17408
	ds_read_b128 v[186:189], v210 offset:18432
	ds_read_b128 v[190:193], v210 offset:19456
	ds_read_b128 v[194:197], v210 offset:20480
	ds_read_b128 v[198:201], v210 offset:21504
	ds_read_b128 v[202:205], v210 offset:22528
	ds_read_b128 v[212:215], v210 offset:23552
	s_mov_b32 m0, s56
	s_nop 0
	global_load_lds_dwordx4 v162, s[4:5]
	s_add_i32 m0, s56, 0x2000
	s_nop 0
	global_load_lds_dwordx4 v206, s[4:5]
	s_add_u32 s4, s10, 0x80000
	s_addc_u32 s5, s11, 0
	s_add_i32 s56, s57, s17
	s_mov_b32 m0, s56
	s_nop 0
	global_load_lds_dwordx4 v162, s[4:5]
	s_add_i32 m0, s56, 0x2000
	s_nop 0
	global_load_lds_dwordx4 v206, s[4:5]
	s_mov_b64 s[4:5], s[12:13]
	s_mov_b32 m0, s18
	s_nop 0
	global_load_lds_dwordx4 v1, s[4:5]
	s_mov_b32 m0, s19
	s_nop 0
	global_load_lds_dwordx4 v164, s[4:5]
	s_waitcnt vmcnt(8)
	s_waitcnt lgkmcnt(0)
	s_barrier
; #define PG8_STAGE(bufoff, gbase, voff) do { const char* gb_ = (const char*)(gbase); asm volatile("" : "+s"(gb_)); _Pragma("unroll") for (int _i = 0; _i < 2; ++_i) { unsigned vo_ = (voff)[_i]; asm volatile("" : "+v"(vo_));        \
;         __builtin_amdgcn_global_load_lds((const unsigned*)(gb_ + vo_), (PG8_LAS unsigned*)(lds + (bufoff) + ldsw + _i * 8192), 16, 0, 0); } } while (0)
; #define PG8_LDA(dst, b, h) do { _Pragma("unroll") for (int m = 0; m < 4; ++m) _Pragma("unroll") for (int k = 0; k < 2; ++k) dst[m][k] = *(const PG8_LAS bf16x8*)(lds + PG8_SA(b, h) + aoff + m * 2048 + k * 1024); } while (0)
; #define PG8_LDB(dst, b, h) do { _Pragma("unroll") for (int n = 0; n < 2; ++n) _Pragma("unroll") for (int k = 0; k < 2; ++k) dst[n][k] = *(const PG8_LAS bf16x8*)(lds + PG8_SB(b, h) + boff + n * 2048 + k * 1024); } while (0)
; #define PG8_MMA(ai, bj, At, Bt) do { __builtin_amdgcn_s_setprio(1); _Pragma("unroll") for (int m = 0; m < 4; ++m) _Pragma("unroll") for (int n = 0; n < 2; ++n) _Pragma("unroll") for (int k = 0; k < 2; ++k) \
;         acc[ai][bj][m][n] = __builtin_amdgcn_mfma_f32_16x16x32_bf16(Bt[n][k], At[m][k], acc[ai][bj][m][n], 0, 0, 0); __builtin_amdgcn_s_setprio(0); } while (0)
; #define PG8_WAIT_V(n) asm volatile("s_waitcnt vmcnt(" #n ")" ::: "memory")
; #define PG8_WAIT_L(n) asm volatile("s_waitcnt lgkmcnt(" #n ")" ::: "memory")
; #define PG8_BAR __builtin_amdgcn_s_barrier()
; #define PG8_SCHED __builtin_amdgcn_sched_barrier(0)
; template <class Epi, class Sched, bool ALIGN_EPI = false, bool SP2 = false>
; __device__ __forceinline__ void gemm_phase(PG8_LAS unsigned char* lds, const Gemm g, const Sched& S, const Epi& E) {
;     ...
;             PG8_WAIT_V(8); PG8_WAIT_L(0); PG8_BAR; PG8_MMA(1, 0, At, B0); PG8_MMA(1, 1, At, B1); PG8_BAR; PG8_SCHED;
;             PG8_LDB(B0, 1, 0); PG8_LDB(B1, 1, 1); PG8_SCHED; PG8_LDA(At, 1, 0); PG8_STAGE(PG8_SA(0, 1), a2 + hstep, voffA);
;             PG8_WAIT_V(8); PG8_WAIT_L(0); PG8_BAR; PG8_MMA(0, 0, At, B0); PG8_MMA(0, 1, At, B1); PG8_BAR; PG8_SCHED;
	s_setprio 1
	s_waitcnt lgkmcnt(0)
	v_mfma_f32_16x16x32_bf16 v[110:113], v[26:29], v[178:181], v[110:113]
	v_mfma_f32_16x16x32_bf16 v[110:113], v[30:33], v[182:185], v[110:113]
	v_mfma_f32_16x16x32_bf16 v[94:97], v[26:29], v[186:189], v[94:97]
	v_mfma_f32_16x16x32_bf16 v[94:97], v[30:33], v[190:193], v[94:97]
	v_mfma_f32_16x16x32_bf16 v[86:89], v[26:29], v[194:197], v[86:89]
	v_mfma_f32_16x16x32_bf16 v[86:89], v[30:33], v[198:201], v[86:89]
	v_mfma_f32_16x16x32_bf16 v[26:29], v[26:29], v[202:205], v[78:81]
	v_mfma_f32_16x16x32_bf16 v[26:29], v[30:33], v[212:215], v[26:29]
	v_mfma_f32_16x16x32_bf16 v[106:109], v[98:101], v[178:181], v[106:109]
	v_mfma_f32_16x16x32_bf16 v[106:109], v[102:105], v[182:185], v[106:109]
	v_mfma_f32_16x16x32_bf16 v[90:93], v[98:101], v[186:189], v[90:93]
	v_mfma_f32_16x16x32_bf16 v[90:93], v[102:105], v[190:193], v[90:93]
	v_mfma_f32_16x16x32_bf16 v[82:85], v[98:101], v[194:197], v[82:85]
	v_mfma_f32_16x16x32_bf16 v[82:85], v[102:105], v[198:201], v[82:85]
	v_mfma_f32_16x16x32_bf16 v[30:33], v[98:101], v[202:205], v[74:77]
	v_mfma_f32_16x16x32_bf16 v[30:33], v[102:105], v[212:215], v[30:33]
	s_setprio 0
	s_setprio 1
	v_mfma_f32_16x16x32_bf16 v[38:41], v[146:149], v[178:181], v[38:41]
	v_mfma_f32_16x16x32_bf16 v[38:41], v[150:153], v[182:185], v[38:41]
	v_mfma_f32_16x16x32_bf16 v[22:25], v[146:149], v[186:189], v[22:25]
	v_mfma_f32_16x16x32_bf16 v[22:25], v[150:153], v[190:193], v[22:25]
	v_mfma_f32_16x16x32_bf16 v[14:17], v[146:149], v[194:197], v[14:17]
	v_mfma_f32_16x16x32_bf16 v[14:17], v[150:153], v[198:201], v[14:17]
	v_mfma_f32_16x16x32_bf16 v[6:9], v[146:149], v[202:205], v[6:9]
	v_mfma_f32_16x16x32_bf16 v[6:9], v[150:153], v[212:215], v[6:9]
	v_mfma_f32_16x16x32_bf16 v[34:37], v[154:157], v[178:181], v[34:37]
	v_mfma_f32_16x16x32_bf16 v[34:37], v[158:161], v[182:185], v[34:37]
	v_mfma_f32_16x16x32_bf16 v[18:21], v[154:157], v[186:189], v[18:21]
	v_mfma_f32_16x16x32_bf16 v[18:21], v[158:161], v[190:193], v[18:21]
	v_mfma_f32_16x16x32_bf16 v[10:13], v[154:157], v[194:197], v[10:13]
	v_mfma_f32_16x16x32_bf16 v[10:13], v[158:161], v[198:201], v[10:13]
	v_mfma_f32_16x16x32_bf16 v[2:5], v[154:157], v[202:205], v[2:5]
	v_mfma_f32_16x16x32_bf16 v[2:5], v[158:161], v[212:215], v[2:5]
	s_setprio 0
	s_barrier
	s_add_i32 s56, 0, 0x18000
	s_add_i32 s57, 0, 0x1c000
	ds_read_b128 v[74:77], v244 offset:32768
	ds_read_b128 v[78:81], v244 offset:33792
	ds_read_b128 v[98:101], v244 offset:34816
	ds_read_b128 v[102:105], v244 offset:35840
	ds_read_b128 v[146:149], v244 offset:49152
	ds_read_b128 v[150:153], v244 offset:50176
	ds_read_b128 v[154:157], v244 offset:51200
	ds_read_b128 v[158:161], v244 offset:52224
	s_add_u32 s4, s12, 0x80000
	s_addc_u32 s5, s13, 0
	s_mov_b32 m0, s20
	ds_read_b128 v[178:181], v210 offset:32768
	ds_read_b128 v[182:185], v210 offset:33792
	ds_read_b128 v[186:189], v210 offset:34816
	ds_read_b128 v[190:193], v210 offset:35840
	ds_read_b128 v[194:197], v210 offset:36864
	ds_read_b128 v[198:201], v210 offset:37888
	ds_read_b128 v[202:205], v210 offset:38912
	ds_read_b128 v[212:215], v210 offset:39936
	s_nop 0
	global_load_lds_dwordx4 v1, s[4:5]
	s_mov_b32 m0, s21
	s_nop 0
	global_load_lds_dwordx4 v164, s[4:5]
	s_waitcnt vmcnt(8)
	s_waitcnt lgkmcnt(0)
	s_barrier
	s_setprio 1
	s_waitcnt lgkmcnt(0)
	v_mfma_f32_16x16x32_bf16 v[142:145], v[74:77], v[178:181], v[142:145]
	v_mfma_f32_16x16x32_bf16 v[142:145], v[78:81], v[182:185], v[142:145]
	v_mfma_f32_16x16x32_bf16 v[134:137], v[74:77], v[186:189], v[134:137]
	v_mfma_f32_16x16x32_bf16 v[134:137], v[78:81], v[190:193], v[134:137]
	v_mfma_f32_16x16x32_bf16 v[126:129], v[74:77], v[194:197], v[126:129]
	v_mfma_f32_16x16x32_bf16 v[126:129], v[78:81], v[198:201], v[126:129]
	v_mfma_f32_16x16x32_bf16 v[118:121], v[74:77], v[202:205], v[118:121]
	v_mfma_f32_16x16x32_bf16 v[118:121], v[78:81], v[212:215], v[118:121]
	v_mfma_f32_16x16x32_bf16 v[138:141], v[98:101], v[178:181], v[138:141]
	v_mfma_f32_16x16x32_bf16 v[138:141], v[102:105], v[182:185], v[138:141]
	v_mfma_f32_16x16x32_bf16 v[130:133], v[98:101], v[186:189], v[130:133]
	v_mfma_f32_16x16x32_bf16 v[130:133], v[102:105], v[190:193], v[130:133]
	v_mfma_f32_16x16x32_bf16 v[122:125], v[98:101], v[194:197], v[122:125]
	v_mfma_f32_16x16x32_bf16 v[122:125], v[102:105], v[198:201], v[122:125]
	v_mfma_f32_16x16x32_bf16 v[114:117], v[98:101], v[202:205], v[114:117]
	v_mfma_f32_16x16x32_bf16 v[114:117], v[102:105], v[212:215], v[114:117]
	s_setprio 0
	s_setprio 1
	v_mfma_f32_16x16x32_bf16 v[70:73], v[146:149], v[178:181], v[70:73]
	v_mfma_f32_16x16x32_bf16 v[70:73], v[150:153], v[182:185], v[70:73]
	v_mfma_f32_16x16x32_bf16 v[62:65], v[146:149], v[186:189], v[62:65]
	v_mfma_f32_16x16x32_bf16 v[62:65], v[150:153], v[190:193], v[62:65]
	v_mfma_f32_16x16x32_bf16 v[54:57], v[146:149], v[194:197], v[54:57]
	v_mfma_f32_16x16x32_bf16 v[54:57], v[150:153], v[198:201], v[54:57]
	v_mfma_f32_16x16x32_bf16 v[46:49], v[146:149], v[202:205], v[46:49]
	v_mfma_f32_16x16x32_bf16 v[46:49], v[150:153], v[212:215], v[46:49]
	v_mfma_f32_16x16x32_bf16 v[66:69], v[154:157], v[178:181], v[66:69]
	v_mfma_f32_16x16x32_bf16 v[66:69], v[158:161], v[182:185], v[66:69]
	v_mfma_f32_16x16x32_bf16 v[58:61], v[154:157], v[186:189], v[58:61]
	v_mfma_f32_16x16x32_bf16 v[58:61], v[158:161], v[190:193], v[58:61]
	v_mfma_f32_16x16x32_bf16 v[50:53], v[154:157], v[194:197], v[50:53]
	v_mfma_f32_16x16x32_bf16 v[50:53], v[158:161], v[198:201], v[50:53]
	v_mfma_f32_16x16x32_bf16 v[42:45], v[154:157], v[202:205], v[42:45]
	v_mfma_f32_16x16x32_bf16 v[42:45], v[158:161], v[212:215], v[42:45]
	s_setprio 0
	s_barrier
;     __device__ __forceinline__ void operator()(const f32x4 (&acc)[2][2][4][2], const Unit& u, int wr, int wc, int fr, int fq) const {
;         const int row0 = u.pm * BM + wr * 64 + fr, col0 = u.pn * BM + wc * 32 + 8 * fq, b = (u.pm * BM) / rows_per_batch;
;         const float* g = gate + (size_t)b * gate_bstride + col0;
;         float ssq[2][4];
; #pragma unroll
;         for (int ai = 0; ai < 2; ++ai)
; #pragma unroll
;             for (int m = 0; m < 4; ++m) ssq[ai][m] = 0.f;
;         f32x4 gv[2][2], Gv[2][2];
; #pragma unroll
; template <class Epi, class Sched, bool ALIGN_EPI = false, bool SP2 = false>
; __device__ __forceinline__ void gemm_phase(PG8_LAS unsigned char* lds, const Gemm g, const Sched& S, const Epi& E) {
;     ...
;             PG8_LDA(At, 1, 1); PG8_STAGE(PG8_SB(1, 0), b3, voffB); PG8_STAGE(PG8_SB(1, 1), b3 + hstep, voffB); PG8_STAGE(PG8_SA(1, 0), a3, voffA);
;             PG8_WAIT_V(8); PG8_WAIT_L(0); PG8_BAR; PG8_MMA(1, 0, At, B0); PG8_MMA(1, 1, At, B1); PG8_BAR; PG8_SCHED;
;             } else {
;             PG8_LDB(B0, 0, 0); PG8_SCHED; PG8_LDA(At, 0, 0); PG8_STAGE(PG8_SA(1, 1), a1 + hstep, voffA);
;             PG8_WAIT_L(8); PG8_BAR; PG8_WAIT_L(0); PG8_MMA(0, 0, At, B0); PG8_BAR; PG8_SCHED;
;             PG8_LDB(B1, 0, 1); PG8_STAGE(PG8_SB(0, 0), b2, voffB);
;             PG8_BAR; PG8_WAIT_L(0); PG8_MMA(0, 1, At, B1); PG8_BAR;
;             PG8_LDA(At, 0, 1); PG8_STAGE(PG8_SA(0, 0), a2, voffA);
;             PG8_BAR; PG8_WAIT_L(0); PG8_MMA(1, 0, At, B0); PG8_BAR; PG8_SCHED;
;             PG8_STAGE(PG8_SB(0, 1), b2 + hstep, voffB);
;             PG8_WAIT_V(6); PG8_BAR; PG8_MMA(1, 1, At, B1); PG8_BAR;
;             PG8_LDB(B0, 1, 0); PG8_SCHED; PG8_LDA(At, 1, 0); PG8_STAGE(PG8_SA(0, 1), a2 + hstep, voffA);
;             PG8_WAIT_L(8); PG8_BAR; PG8_WAIT_L(0); PG8_MMA(0, 0, At, B0); PG8_BAR; PG8_SCHED;
;             PG8_LDB(B1, 1, 1); PG8_STAGE(PG8_SB(1, 0), b3, voffB);
;             PG8_BAR; PG8_WAIT_L(0); PG8_MMA(0, 1, At, B1); PG8_BAR;
;             PG8_LDA(At, 1, 1); PG8_STAGE(PG8_SA(1, 0), a3, voffA);
;             PG8_BAR; PG8_WAIT_L(0); PG8_MMA(1, 0, At, B0); PG8_BAR; PG8_SCHED;
;             PG8_STAGE(PG8_SB(1, 1), b3 + hstep, voffB);
;             PG8_WAIT_V(6); PG8_BAR; PG8_MMA(1, 1, At, B1); PG8_BAR;
;             }
;         }
;         if constexpr (ALIGN_EPI) { if (wr == 0) PG8_BAR; }
	s_add_u32 s4, s10, 0x80
	s_addc_u32 s5, s11, 0
	s_add_i32 s12, s56, s17
	ds_read_b128 v[178:181], v210 offset:49152
	ds_read_b128 v[182:185], v210 offset:50176
	ds_read_b128 v[186:189], v210 offset:51200
	ds_read_b128 v[190:193], v210 offset:52224
	ds_read_b128 v[194:197], v210 offset:53248
	ds_read_b128 v[198:201], v210 offset:54272
	ds_read_b128 v[202:205], v210 offset:55296
	ds_read_b128 v[212:215], v210 offset:56320
	s_mov_b32 m0, s12
	s_nop 0
	global_load_lds_dwordx4 v162, s[4:5]
	s_add_i32 m0, s12, 0x2000
	s_nop 0
	global_load_lds_dwordx4 v206, s[4:5]
	s_add_u32 s4, s10, 0x80080
	s_addc_u32 s5, s11, 0
	s_add_i32 s10, s57, s17
	s_mov_b32 m0, s10
	s_nop 0
	global_load_lds_dwordx4 v162, s[4:5]
	s_add_i32 m0, s10, 0x2000
	s_nop 0
	global_load_lds_dwordx4 v206, s[4:5]
	s_mov_b32 m0, s26
	s_nop 0
	global_load_lds_dwordx4 v1, s[8:9]
	s_mov_b32 m0, s27
	s_nop 0
	global_load_lds_dwordx4 v164, s[8:9]
	s_waitcnt vmcnt(8)
	s_waitcnt lgkmcnt(0)
	s_barrier
	s_setprio 1
	s_waitcnt lgkmcnt(0)
	v_mfma_f32_16x16x32_bf16 v[110:113], v[74:77], v[178:181], v[110:113]
	v_mfma_f32_16x16x32_bf16 v[110:113], v[78:81], v[182:185], v[110:113]
	v_mfma_f32_16x16x32_bf16 v[94:97], v[74:77], v[186:189], v[94:97]
	v_mfma_f32_16x16x32_bf16 v[94:97], v[78:81], v[190:193], v[94:97]
	v_mfma_f32_16x16x32_bf16 v[86:89], v[74:77], v[194:197], v[86:89]
	v_mfma_f32_16x16x32_bf16 v[86:89], v[78:81], v[198:201], v[86:89]
	v_mfma_f32_16x16x32_bf16 v[26:29], v[74:77], v[202:205], v[26:29]
	v_mfma_f32_16x16x32_bf16 v[78:81], v[78:81], v[212:215], v[26:29]
	v_mfma_f32_16x16x32_bf16 v[106:109], v[98:101], v[178:181], v[106:109]
	v_mfma_f32_16x16x32_bf16 v[106:109], v[102:105], v[182:185], v[106:109]
	v_mfma_f32_16x16x32_bf16 v[90:93], v[98:101], v[186:189], v[90:93]
	v_mfma_f32_16x16x32_bf16 v[90:93], v[102:105], v[190:193], v[90:93]
	v_mfma_f32_16x16x32_bf16 v[82:85], v[98:101], v[194:197], v[82:85]
	v_mfma_f32_16x16x32_bf16 v[82:85], v[102:105], v[198:201], v[82:85]
	v_mfma_f32_16x16x32_bf16 v[26:29], v[98:101], v[202:205], v[30:33]
	v_mfma_f32_16x16x32_bf16 v[74:77], v[102:105], v[212:215], v[26:29]
	s_setprio 0
	s_setprio 1
	v_mfma_f32_16x16x32_bf16 v[26:29], v[146:149], v[178:181], v[38:41]
	v_mfma_f32_16x16x32_bf16 v[38:41], v[150:153], v[182:185], v[26:29]
	v_mfma_f32_16x16x32_bf16 v[22:25], v[146:149], v[186:189], v[22:25]
	v_mfma_f32_16x16x32_bf16 v[22:25], v[150:153], v[190:193], v[22:25]
	v_mfma_f32_16x16x32_bf16 v[14:17], v[146:149], v[194:197], v[14:17]
	v_mfma_f32_16x16x32_bf16 v[14:17], v[150:153], v[198:201], v[14:17]
	v_mfma_f32_16x16x32_bf16 v[6:9], v[146:149], v[202:205], v[6:9]
	v_mfma_f32_16x16x32_bf16 v[6:9], v[150:153], v[212:215], v[6:9]
	v_mfma_f32_16x16x32_bf16 v[26:29], v[154:157], v[178:181], v[34:37]
	v_mfma_f32_16x16x32_bf16 v[34:37], v[158:161], v[182:185], v[26:29]
	v_mfma_f32_16x16x32_bf16 v[18:21], v[154:157], v[186:189], v[18:21]
	v_mfma_f32_16x16x32_bf16 v[18:21], v[158:161], v[190:193], v[18:21]
	v_mfma_f32_16x16x32_bf16 v[10:13], v[154:157], v[194:197], v[10:13]
	v_mfma_f32_16x16x32_bf16 v[10:13], v[158:161], v[198:201], v[10:13]
	v_mfma_f32_16x16x32_bf16 v[2:5], v[154:157], v[202:205], v[2:5]
	v_mfma_f32_16x16x32_bf16 v[2:5], v[158:161], v[212:215], v[2:5]
	s_setprio 0
	s_barrier
	s_add_i32 s51, s51, 2
	s_add_u32 s40, s40, 0x100
	s_addc_u32 s49, s49, 0
	s_cmp_gt_u32 s51, 29
	s_mov_b64 s[4:5], s[6:7]
	s_cbranch_scc0 .LBB0_555
	s_cmp_lg_u32 s98, 0
	s_cbranch_scc1 .Lal_1
	s_barrier
.Lal_1:
	s_ashr_i32 s4, s29, 31
	s_lshr_b32 s4, s4, 27
	s_add_i32 s4, s29, s4
	s_ashr_i32 s4, s4, 5
	v_lshl_or_b32 v148, s33, 8, v209
	s_mul_i32 s7, s4, 0xc000
	v_ashrrev_i32_e32 v149, 31, v148
	s_mul_hi_i32 s6, s4, 0xc000
	s_add_u32 s4, s22, s7
	s_addc_u32 s5, s23, s6
	v_lshlrev_b64 v[26:27], 2, v[148:149]
	v_lshl_add_u64 v[146:147], s[4:5], 0, v[26:27]
	s_add_u32 s4, s24, s7
	s_addc_u32 s5, s25, s6
	v_lshl_add_u64 v[160:161], s[4:5], 0, v[26:27]
	v_lshl_add_u64 v[178:179], s[46:47], 0, v[26:27]
	global_load_dwordx4 v[98:101], v[146:147], off offset:16
	global_load_dwordx4 v[102:105], v[146:147], off
	global_load_dwordx4 v[26:29], v[178:179], off offset:16
	global_load_dwordx4 v[30:33], v[178:179], off
	global_load_dwordx4 v[150:153], v[160:161], off offset:16
	global_load_dwordx4 v[154:157], v[160:161], off
	s_mov_b64 s[4:5], 0x40000
	s_waitcnt vmcnt(0)
	v_pk_mul_f32 v[188:189], v[140:141], v[100:101]
	v_pk_mul_f32 v[142:143], v[142:143], v[102:103]
	v_pk_mul_f32 v[144:145], v[144:145], v[104:105]
	v_pk_mul_f32 v[140:141], v[138:139], v[98:99]
	v_pk_mul_f32 v[136:137], v[136:137], v[104:105]
	v_pk_add_f32 v[156:157], v[156:157], 1.0 op_sel_hi:[1,0]
	v_pk_add_f32 v[154:155], v[154:155], 1.0 op_sel_hi:[1,0]
	v_pk_mul_f32 v[198:199], v[32:33], v[156:157]
	v_pk_mul_f32 v[200:201], v[30:31], v[154:155]
	v_pk_add_f32 v[30:31], v[152:153], 1.0 op_sel_hi:[1,0]
	v_pk_add_f32 v[32:33], v[150:151], 1.0 op_sel_hi:[1,0]
	v_pk_mul_f32 v[202:203], v[28:29], v[30:31]
	v_pk_mul_f32 v[204:205], v[26:27], v[32:33]
	global_load_dwordx4 v[26:29], v[146:147], off offset:528
	global_load_dwordx4 v[30:33], v[146:147], off offset:512
	global_load_dwordx4 v[156:159], v[178:179], off offset:528
	global_load_dwordx4 v[152:155], v[178:179], off offset:512
	s_nop 0
	global_load_dwordx4 v[178:181], v[160:161], off offset:528
	global_load_dwordx4 v[182:185], v[160:161], off offset:512
	v_pk_mul_f32 v[134:135], v[134:135], v[102:103]
	v_pk_mul_f32 v[130:131], v[130:131], v[98:99]
	v_pk_mul_f32 v[132:133], v[132:133], v[100:101]
	v_pk_mul_f32 v[128:129], v[128:129], v[104:105]
	v_pk_mul_f32 v[126:127], v[126:127], v[102:103]
	v_pk_mul_f32 v[122:123], v[122:123], v[98:99]
	v_pk_mul_f32 v[124:125], v[124:125], v[100:101]
	v_pk_mul_f32 v[120:121], v[120:121], v[104:105]
	v_pk_mul_f32 v[118:119], v[118:119], v[102:103]
	v_pk_mul_f32 v[114:115], v[114:115], v[98:99]
	v_pk_mul_f32 v[116:117], v[116:117], v[100:101]
	v_pk_mul_f32 v[112:113], v[112:113], v[104:105]
	v_pk_mul_f32 v[110:111], v[110:111], v[102:103]
	v_pk_mul_f32 v[106:107], v[106:107], v[98:99]
	v_pk_mul_f32 v[108:109], v[108:109], v[100:101]
	v_pk_mul_f32 v[96:97], v[96:97], v[104:105]
	v_pk_mul_f32 v[94:95], v[94:95], v[102:103]
	v_pk_mul_f32 v[90:91], v[90:91], v[98:99]
	v_pk_mul_f32 v[92:93], v[92:93], v[100:101]
	v_pk_mul_f32 v[88:89], v[88:89], v[104:105]
	v_pk_mul_f32 v[86:87], v[86:87], v[102:103]
	v_pk_mul_f32 v[82:83], v[82:83], v[98:99]
	v_pk_mul_f32 v[84:85], v[84:85], v[100:101]
	v_pk_mul_f32 v[80:81], v[80:81], v[104:105]
	v_pk_mul_f32 v[78:79], v[78:79], v[102:103]
	v_pk_mul_f32 v[74:75], v[74:75], v[98:99]
	v_pk_mul_f32 v[76:77], v[76:77], v[100:101]
	s_waitcnt vmcnt(5)
; __device__ __forceinline__ unsigned cvt_pk_bf16(float lo, float hi) { unsigned r; asm volatile("v_cvt_pk_bf16_f32 %0, %1, %2" : "=v"(r) : "v"(lo), "v"(hi)); return r; }
;     __device__ __forceinline__ void operator()(const f32x4 (&acc)[2][2][4][2], const Unit& u, int wr, int wc, int fr, int fq) const {
;     ...
;                 for (int m = 0; m < 4; ++m) { const size_t off = (size_t)(row0 + ai * HALF + m * 16) * 2048 + col0 + bj * HALF;
;                     f32x4 x0 = __builtin_nontemporal_load((const f32x4*)(base + off)), x1 = __builtin_nontemporal_load((const f32x4*)(base + off + 4));
;                     if constexpr (HAS_DIN) { const u32x4 dw = __builtin_nontemporal_load((const u32x4*)(dbuf + off));
;                         x0 += (f32x4){__builtin_bit_cast(float, dw.x << 16), __builtin_bit_cast(float, dw.x & 0xffff0000u), __builtin_bit_cast(float, dw.y << 16), __builtin_bit_cast(float, dw.y & 0xffff0000u)};
;                         x1 += (f32x4){__builtin_bit_cast(float, dw.z << 16), __builtin_bit_cast(float, dw.z & 0xffff0000u), __builtin_bit_cast(float, dw.w << 16), __builtin_bit_cast(float, dw.w & 0xffff0000u)}; }
;                     f32x4 o0, o1;
;                     if constexpr (OUT_DELTA) { const f32x4 d0 = g0 * acc[ai][bj][m][0], d1 = g1 * acc[ai][bj][m][1];
;                         u32x4 w; w.x = cvt_pk_bf16(d0[0], d0[1]); w.y = cvt_pk_bf16(d0[2], d0[3]); w.z = cvt_pk_bf16(d1[0], d1[1]); w.w = cvt_pk_bf16(d1[2], d1[3]);
;                         *(u32x4*)(dbuf + off) = w;
;                         o0 = x0 + (f32x4){__builtin_bit_cast(float, w.x << 16), __builtin_bit_cast(float, w.x & 0xffff0000u), __builtin_bit_cast(float, w.y << 16), __builtin_bit_cast(float, w.y & 0xffff0000u)};
;                         o1 = x1 + (f32x4){__builtin_bit_cast(float, w.z << 16), __builtin_bit_cast(float, w.z & 0xffff0000u), __builtin_bit_cast(float, w.w << 16), __builtin_bit_cast(float, w.w & 0xffff0000u)}; }
;                     else { o0 = x0 + g0 * acc[ai][bj][m][0]; o1 = x1 + g1 * acc[ai][bj][m][1]; *(f32x4*)(out + off) = o0; *(f32x4*)(out + off + 4) = o1; }
;                     if (Hn) { const f32x4 h0 = o0 * G0, h1 = o1 * G1;
;                         u32x4 w; w.x = cvt_pk_bf16(h0[0], h0[1]); w.y = cvt_pk_bf16(h0[2], h0[3]); w.z = cvt_pk_bf16(h1[0], h1[1]); w.w = cvt_pk_bf16(h1[2], h1[3]);
;                         *(u32x4*)(Hn + off) = w;
	v_pk_mul_f32 v[58:59], v[58:59], v[26:27]
	s_waitcnt vmcnt(4)
	v_pk_mul_f32 v[72:73], v[72:73], v[32:33]
	v_pk_mul_f32 v[70:71], v[70:71], v[30:31]
	v_pk_mul_f32 v[64:65], v[64:65], v[32:33]
	v_pk_mul_f32 v[62:63], v[62:63], v[30:31]
	s_waitcnt vmcnt(0)
	v_pk_add_f32 v[146:147], v[184:185], 1.0 op_sel_hi:[1,0]
	v_pk_add_f32 v[160:161], v[182:183], 1.0 op_sel_hi:[1,0]
	v_pk_mul_f32 v[150:151], v[154:155], v[146:147]
	v_pk_add_f32 v[146:147], v[180:181], 1.0 op_sel_hi:[1,0]
	v_pk_mul_f32 v[152:153], v[152:153], v[160:161]
	v_pk_mul_f32 v[154:155], v[158:159], v[146:147]
	v_lshl_add_u32 v146, s29, 8, v207
	v_ashrrev_i32_e32 v147, 31, v146
	v_lshlrev_b64 v[184:185], 11, v[146:147]
	v_lshl_add_u64 v[186:187], v[184:185], 0, v[148:149]
	v_pk_add_f32 v[160:161], v[178:179], 1.0 op_sel_hi:[1,0]
	v_lshl_add_u64 v[178:179], v[186:187], 2, s[44:45]
	v_pk_mul_f32 v[156:157], v[156:157], v[160:161]
	global_load_dwordx4 v[158:161], v[178:179], off nt
	global_load_dwordx4 v[180:183], v[178:179], off offset:16 nt
	v_cvt_pk_bf16_f32 v138, v142, v143
	v_lshlrev_b64 v[142:143], 1, v[186:187]
	v_cvt_pk_bf16_f32 v139, v144, v145
	v_cvt_pk_bf16_f32 v140, v140, v141
	v_cvt_pk_bf16_f32 v141, v188, v189
	v_lshl_add_u64 v[144:145], s[90:91], 0, v[142:143]
	global_store_dwordx4 v[144:145], v[138:141], off
	v_lshlrev_b32_e32 v144, 16, v140
	v_and_b32_e32 v145, 0xffff0000, v140
	v_lshlrev_b32_e32 v140, 16, v141
	v_and_b32_e32 v141, 0xffff0000, v141
	v_lshl_add_u64 v[142:143], s[96:97], 0, v[142:143]
	v_pk_mul_f32 v[60:61], v[60:61], v[28:29]
	v_pk_mul_f32 v[56:57], v[56:57], v[32:33]
	v_pk_mul_f32 v[54:55], v[54:55], v[30:31]
	v_pk_mul_f32 v[50:51], v[50:51], v[26:27]
	v_pk_mul_f32 v[52:53], v[52:53], v[28:29]
	v_pk_mul_f32 v[48:49], v[48:49], v[32:33]
	v_pk_mul_f32 v[46:47], v[46:47], v[30:31]
	v_pk_mul_f32 v[42:43], v[42:43], v[26:27]
	v_pk_mul_f32 v[44:45], v[44:45], v[28:29]
	v_pk_mul_f32 v[40:41], v[40:41], v[32:33]
	v_pk_mul_f32 v[38:39], v[38:39], v[30:31]
	v_pk_mul_f32 v[34:35], v[34:35], v[26:27]
	v_pk_mul_f32 v[36:37], v[36:37], v[28:29]
	v_pk_mul_f32 v[24:25], v[24:25], v[32:33]
	v_pk_mul_f32 v[22:23], v[22:23], v[30:31]
	v_pk_mul_f32 v[18:19], v[18:19], v[26:27]
	v_pk_mul_f32 v[20:21], v[20:21], v[28:29]
	v_pk_mul_f32 v[16:17], v[16:17], v[32:33]
	v_pk_mul_f32 v[14:15], v[14:15], v[30:31]
	v_pk_mul_f32 v[10:11], v[10:11], v[26:27]
	v_pk_mul_f32 v[12:13], v[12:13], v[28:29]
	v_pk_mul_f32 v[8:9], v[8:9], v[32:33]
	v_pk_mul_f32 v[6:7], v[6:7], v[30:31]
	v_pk_mul_f32 v[2:3], v[2:3], v[26:27]
	v_pk_mul_f32 v[4:5], v[4:5], v[28:29]
	s_waitcnt vmcnt(1)
	v_pk_add_f32 v[182:183], v[182:183], v[140:141]
	v_lshlrev_b32_e32 v140, 16, v138
	v_and_b32_e32 v141, 0xffff0000, v138
	v_lshlrev_b32_e32 v138, 16, v139
	v_and_b32_e32 v139, 0xffff0000, v139
	v_pk_add_f32 v[158:159], v[158:159], v[140:141]
	v_pk_add_f32 v[160:161], v[160:161], v[138:139]
	v_pk_mul_f32 v[138:139], v[200:201], v[158:159]
	v_pk_add_f32 v[144:145], v[180:181], v[144:145]
	v_pk_mul_f32 v[140:141], v[198:199], v[160:161]
	v_cvt_pk_bf16_f32 v138, v138, v139
	v_pk_mul_f32 v[180:181], v[202:203], v[182:183]
	v_cvt_pk_bf16_f32 v139, v140, v141
	v_pk_mul_f32 v[186:187], v[204:205], v[144:145]
	s_nop 0
	v_cvt_pk_bf16_f32 v140, v186, v187
	v_cvt_pk_bf16_f32 v141, v180, v181
	global_store_dwordx4 v[142:143], v[138:141], off
	s_nop 1
	v_mul_f32_e32 v138, v159, v159
	v_mul_f32_e32 v139, v161, v161
	v_fmac_f32_e32 v138, v158, v158
	v_fmac_f32_e32 v139, v160, v160
	v_add_f32_e32 v138, v138, v139
	v_mul_f32_e32 v139, v145, v145
	v_mul_f32_e32 v140, v183, v183
	v_fmac_f32_e32 v139, v144, v144
	v_fmac_f32_e32 v140, v182, v182
	v_add_f32_e32 v139, v139, v140
	v_add_f32_e32 v211, v138, v139
	v_or_b32_e32 v138, 16, v146
	v_ashrrev_i32_e32 v139, 31, v138
	v_lshlrev_b64 v[140:141], 11, v[138:139]
	v_lshl_add_u64 v[180:181], v[140:141], 0, v[148:149]
	v_lshl_add_u64 v[138:139], v[180:181], 2, s[44:45]
	global_load_dwordx4 v[142:145], v[138:139], off nt
	global_load_dwordx4 v[158:161], v[138:139], off offset:16 nt
	v_lshlrev_b64 v[180:181], 1, v[180:181]
	v_cvt_pk_bf16_f32 v134, v134, v135
	v_cvt_pk_bf16_f32 v135, v136, v137
	v_cvt_pk_bf16_f32 v136, v130, v131
	v_cvt_pk_bf16_f32 v137, v132, v133
	v_lshl_add_u64 v[130:131], s[90:91], 0, v[180:181]
	global_store_dwordx4 v[130:131], v[134:137], off
	v_lshlrev_b32_e32 v132, 16, v136
	v_and_b32_e32 v133, 0xffff0000, v136
	v_lshlrev_b32_e32 v130, 16, v137
	v_and_b32_e32 v131, 0xffff0000, v137
	v_lshlrev_b32_e32 v136, 16, v134
	v_and_b32_e32 v137, 0xffff0000, v134
	v_lshlrev_b32_e32 v134, 16, v135
	v_and_b32_e32 v135, 0xffff0000, v135
	s_waitcnt vmcnt(2)
	v_pk_add_f32 v[134:135], v[144:145], v[134:135]
	s_waitcnt vmcnt(1)
	v_pk_add_f32 v[130:131], v[160:161], v[130:131]
	v_pk_add_f32 v[136:137], v[142:143], v[136:137]
	v_pk_add_f32 v[132:133], v[158:159], v[132:133]
	v_pk_mul_f32 v[144:145], v[198:199], v[134:135]
	v_pk_mul_f32 v[142:143], v[200:201], v[136:137]
	v_pk_mul_f32 v[158:159], v[202:203], v[130:131]
	v_pk_mul_f32 v[160:161], v[204:205], v[132:133]
	v_cvt_pk_bf16_f32 v142, v142, v143
	v_cvt_pk_bf16_f32 v143, v144, v145
	s_nop 0
	v_cvt_pk_bf16_f32 v144, v160, v161
	v_cvt_pk_bf16_f32 v145, v158, v159
	v_lshl_add_u64 v[158:159], s[96:97], 0, v[180:181]
	global_store_dwordx4 v[158:159], v[142:145], off
	s_nop 1
	v_or_b32_e32 v142, 32, v146
	v_ashrrev_i32_e32 v143, 31, v142
	v_lshlrev_b64 v[144:145], 11, v[142:143]
	v_lshl_add_u64 v[186:187], v[144:145], 0, v[148:149]
	v_lshl_add_u64 v[142:143], v[186:187], 2, s[44:45]
	global_load_dwordx4 v[158:161], v[142:143], off nt
	global_load_dwordx4 v[180:183], v[142:143], off offset:16 nt
	v_lshlrev_b64 v[186:187], 1, v[186:187]
	v_cvt_pk_bf16_f32 v126, v126, v127
	v_cvt_pk_bf16_f32 v127, v128, v129
	v_cvt_pk_bf16_f32 v128, v122, v123
	v_cvt_pk_bf16_f32 v129, v124, v125
	v_lshl_add_u64 v[122:123], s[90:91], 0, v[186:187]
	global_store_dwordx4 v[122:123], v[126:129], off
	v_lshlrev_b32_e32 v124, 16, v128
	v_and_b32_e32 v125, 0xffff0000, v128
	v_lshlrev_b32_e32 v122, 16, v129
	v_and_b32_e32 v123, 0xffff0000, v129
	v_lshlrev_b32_e32 v128, 16, v126
	v_and_b32_e32 v129, 0xffff0000, v126
	v_lshlrev_b32_e32 v126, 16, v127
	v_and_b32_e32 v127, 0xffff0000, v127
	s_waitcnt vmcnt(2)
; __device__ __forceinline__ unsigned cvt_pk_bf16(float lo, float hi) { unsigned r; asm volatile("v_cvt_pk_bf16_f32 %0, %1, %2" : "=v"(r) : "v"(lo), "v"(hi)); return r; }
;     __device__ __forceinline__ void operator()(const f32x4 (&acc)[2][2][4][2], const Unit& u, int wr, int wc, int fr, int fq) const {
;     ...
;                 for (int m = 0; m < 4; ++m) { const size_t off = (size_t)(row0 + ai * HALF + m * 16) * 2048 + col0 + bj * HALF;
;                     f32x4 x0 = __builtin_nontemporal_load((const f32x4*)(base + off)), x1 = __builtin_nontemporal_load((const f32x4*)(base + off + 4));
;                     if constexpr (HAS_DIN) { const u32x4 dw = __builtin_nontemporal_load((const u32x4*)(dbuf + off));
;                         x0 += (f32x4){__builtin_bit_cast(float, dw.x << 16), __builtin_bit_cast(float, dw.x & 0xffff0000u), __builtin_bit_cast(float, dw.y << 16), __builtin_bit_cast(float, dw.y & 0xffff0000u)};
;                         x1 += (f32x4){__builtin_bit_cast(float, dw.z << 16), __builtin_bit_cast(float, dw.z & 0xffff0000u), __builtin_bit_cast(float, dw.w << 16), __builtin_bit_cast(float, dw.w & 0xffff0000u)}; }
;                     f32x4 o0, o1;
;                     if constexpr (OUT_DELTA) { const f32x4 d0 = g0 * acc[ai][bj][m][0], d1 = g1 * acc[ai][bj][m][1];
;                         u32x4 w; w.x = cvt_pk_bf16(d0[0], d0[1]); w.y = cvt_pk_bf16(d0[2], d0[3]); w.z = cvt_pk_bf16(d1[0], d1[1]); w.w = cvt_pk_bf16(d1[2], d1[3]);
;                         *(u32x4*)(dbuf + off) = w;
;                         o0 = x0 + (f32x4){__builtin_bit_cast(float, w.x << 16), __builtin_bit_cast(float, w.x & 0xffff0000u), __builtin_bit_cast(float, w.y << 16), __builtin_bit_cast(float, w.y & 0xffff0000u)};
;                         o1 = x1 + (f32x4){__builtin_bit_cast(float, w.z << 16), __builtin_bit_cast(float, w.z & 0xffff0000u), __builtin_bit_cast(float, w.w << 16), __builtin_bit_cast(float, w.w & 0xffff0000u)}; }
;                     else { o0 = x0 + g0 * acc[ai][bj][m][0]; o1 = x1 + g1 * acc[ai][bj][m][1]; *(f32x4*)(out + off) = o0; *(f32x4*)(out + off + 4) = o1; }
;                     if (Hn) { const f32x4 h0 = o0 * G0, h1 = o1 * G1;
;                         u32x4 w; w.x = cvt_pk_bf16(h0[0], h0[1]); w.y = cvt_pk_bf16(h0[2], h0[3]); w.z = cvt_pk_bf16(h1[0], h1[1]); w.w = cvt_pk_bf16(h1[2], h1[3]);
;                         *(u32x4*)(Hn + off) = w;
	v_pk_add_f32 v[126:127], v[160:161], v[126:127]
	s_waitcnt vmcnt(1)
	v_pk_add_f32 v[122:123], v[182:183], v[122:123]
	v_pk_add_f32 v[128:129], v[158:159], v[128:129]
	v_pk_add_f32 v[124:125], v[180:181], v[124:125]
	v_pk_mul_f32 v[160:161], v[198:199], v[126:127]
	v_pk_mul_f32 v[158:159], v[200:201], v[128:129]
	v_pk_mul_f32 v[180:181], v[202:203], v[122:123]
	v_pk_mul_f32 v[182:183], v[204:205], v[124:125]
	v_cvt_pk_bf16_f32 v158, v158, v159
	v_cvt_pk_bf16_f32 v159, v160, v161
	s_nop 0
	v_cvt_pk_bf16_f32 v160, v182, v183
	v_cvt_pk_bf16_f32 v161, v180, v181
	v_lshl_add_u64 v[180:181], s[96:97], 0, v[186:187]
	global_store_dwordx4 v[180:181], v[158:161], off
	s_nop 1
	v_or_b32_e32 v158, 48, v146
	v_ashrrev_i32_e32 v159, 31, v158
	v_lshlrev_b64 v[160:161], 11, v[158:159]
	v_lshl_add_u64 v[190:191], v[160:161], 0, v[148:149]
	v_lshl_add_u64 v[158:159], v[190:191], 2, s[44:45]
	global_load_dwordx4 v[180:183], v[158:159], off nt
	global_load_dwordx4 v[186:189], v[158:159], off offset:16 nt
	v_lshlrev_b64 v[190:191], 1, v[190:191]
	v_cvt_pk_bf16_f32 v118, v118, v119
	v_cvt_pk_bf16_f32 v119, v120, v121
	v_cvt_pk_bf16_f32 v120, v114, v115
	v_cvt_pk_bf16_f32 v121, v116, v117
	v_lshl_add_u64 v[114:115], s[90:91], 0, v[190:191]
	global_store_dwordx4 v[114:115], v[118:121], off
	v_lshlrev_b32_e32 v116, 16, v120
	v_and_b32_e32 v117, 0xffff0000, v120
	v_lshlrev_b32_e32 v114, 16, v121
	v_and_b32_e32 v115, 0xffff0000, v121
	v_lshlrev_b32_e32 v120, 16, v118
	v_and_b32_e32 v121, 0xffff0000, v118
	v_lshlrev_b32_e32 v118, 16, v119
	v_and_b32_e32 v119, 0xffff0000, v119
	s_waitcnt vmcnt(2)
	v_pk_add_f32 v[118:119], v[182:183], v[118:119]
	s_waitcnt vmcnt(1)
	v_pk_add_f32 v[114:115], v[188:189], v[114:115]
	v_pk_add_f32 v[120:121], v[180:181], v[120:121]
	v_pk_add_f32 v[116:117], v[186:187], v[116:117]
	v_pk_mul_f32 v[182:183], v[198:199], v[118:119]
	v_pk_mul_f32 v[180:181], v[200:201], v[120:121]
	v_pk_mul_f32 v[186:187], v[202:203], v[114:115]
	v_pk_mul_f32 v[188:189], v[204:205], v[116:117]
	v_cvt_pk_bf16_f32 v180, v180, v181
	v_cvt_pk_bf16_f32 v181, v182, v183
	s_nop 0
	v_cvt_pk_bf16_f32 v182, v188, v189
	v_cvt_pk_bf16_f32 v183, v186, v187
	v_lshl_add_u64 v[186:187], s[96:97], 0, v[190:191]
	global_store_dwordx4 v[186:187], v[180:183], off
	s_nop 1
	v_lshl_add_u64 v[182:183], v[184:185], 0, s[4:5]
	v_lshl_add_u64 v[194:195], v[182:183], 0, v[148:149]
	v_lshl_add_u64 v[180:181], v[194:195], 2, s[44:45]
	global_load_dwordx4 v[186:189], v[180:181], off nt
	global_load_dwordx4 v[190:193], v[180:181], off offset:16 nt
	v_lshlrev_b64 v[194:195], 1, v[194:195]
	v_cvt_pk_bf16_f32 v110, v110, v111
	v_cvt_pk_bf16_f32 v111, v112, v113
	v_cvt_pk_bf16_f32 v112, v106, v107
	v_cvt_pk_bf16_f32 v113, v108, v109
	v_lshl_add_u64 v[106:107], s[90:91], 0, v[194:195]
	global_store_dwordx4 v[106:107], v[110:113], off
	v_lshlrev_b32_e32 v108, 16, v112
	v_and_b32_e32 v109, 0xffff0000, v112
	v_lshlrev_b32_e32 v106, 16, v113
	v_and_b32_e32 v107, 0xffff0000, v113
	v_lshlrev_b32_e32 v112, 16, v110
	v_and_b32_e32 v113, 0xffff0000, v110
	v_lshlrev_b32_e32 v110, 16, v111
	v_and_b32_e32 v111, 0xffff0000, v111
	s_mov_b64 s[4:5], 0x48000
	s_waitcnt vmcnt(2)
	v_pk_add_f32 v[110:111], v[188:189], v[110:111]
	s_waitcnt vmcnt(1)
	v_pk_add_f32 v[106:107], v[192:193], v[106:107]
	v_pk_add_f32 v[112:113], v[186:187], v[112:113]
	v_pk_add_f32 v[108:109], v[190:191], v[108:109]
	v_pk_mul_f32 v[188:189], v[198:199], v[110:111]
	v_pk_mul_f32 v[186:187], v[200:201], v[112:113]
	v_pk_mul_f32 v[190:191], v[202:203], v[106:107]
	v_pk_mul_f32 v[192:193], v[204:205], v[108:109]
	v_cvt_pk_bf16_f32 v186, v186, v187
	v_cvt_pk_bf16_f32 v187, v188, v189
	s_nop 0
	v_cvt_pk_bf16_f32 v188, v192, v193
	v_cvt_pk_bf16_f32 v189, v190, v191
	v_lshl_add_u64 v[190:191], s[96:97], 0, v[194:195]
	global_store_dwordx4 v[190:191], v[186:189], off
	s_nop 1
	v_lshl_add_u64 v[188:189], v[184:185], 0, s[4:5]
	v_lshl_add_u64 v[212:213], v[188:189], 0, v[148:149]
	v_lshl_add_u64 v[186:187], v[212:213], 2, s[44:45]
	global_load_dwordx4 v[190:193], v[186:187], off nt
	global_load_dwordx4 v[194:197], v[186:187], off offset:16 nt
	v_lshlrev_b64 v[212:213], 1, v[212:213]
	v_cvt_pk_bf16_f32 v94, v94, v95
	v_cvt_pk_bf16_f32 v95, v96, v97
	v_cvt_pk_bf16_f32 v96, v90, v91
	v_cvt_pk_bf16_f32 v97, v92, v93
	v_lshl_add_u64 v[90:91], s[90:91], 0, v[212:213]
	global_store_dwordx4 v[90:91], v[94:97], off
	v_lshlrev_b32_e32 v92, 16, v96
	v_and_b32_e32 v93, 0xffff0000, v96
	v_lshlrev_b32_e32 v90, 16, v97
	v_and_b32_e32 v91, 0xffff0000, v97
	v_lshlrev_b32_e32 v96, 16, v94
	v_and_b32_e32 v97, 0xffff0000, v94
	v_lshlrev_b32_e32 v94, 16, v95
	v_and_b32_e32 v95, 0xffff0000, v95
	s_mov_b64 s[4:5], 0x50000
	s_waitcnt vmcnt(2)
	v_pk_add_f32 v[94:95], v[192:193], v[94:95]
	s_waitcnt vmcnt(1)
	v_pk_add_f32 v[90:91], v[196:197], v[90:91]
	v_pk_add_f32 v[96:97], v[190:191], v[96:97]
	v_pk_add_f32 v[92:93], v[194:195], v[92:93]
	v_pk_mul_f32 v[192:193], v[198:199], v[94:95]
	v_pk_mul_f32 v[190:191], v[200:201], v[96:97]
	v_pk_mul_f32 v[194:195], v[202:203], v[90:91]
	v_pk_mul_f32 v[196:197], v[204:205], v[92:93]
	v_cvt_pk_bf16_f32 v190, v190, v191
	v_cvt_pk_bf16_f32 v191, v192, v193
	s_nop 0
	v_cvt_pk_bf16_f32 v192, v196, v197
	v_cvt_pk_bf16_f32 v193, v194, v195
	v_lshl_add_u64 v[194:195], s[96:97], 0, v[212:213]
	global_store_dwordx4 v[194:195], v[190:193], off
	s_nop 1
	v_lshl_add_u64 v[192:193], v[184:185], 0, s[4:5]
	v_lshl_add_u64 v[220:221], v[192:193], 0, v[148:149]
	v_lshl_add_u64 v[190:191], v[220:221], 2, s[44:45]
	global_load_dwordx4 v[194:197], v[190:191], off nt
	global_load_dwordx4 v[212:215], v[190:191], off offset:16 nt
	v_lshlrev_b64 v[220:221], 1, v[220:221]
	v_cvt_pk_bf16_f32 v86, v86, v87
	v_cvt_pk_bf16_f32 v87, v88, v89
	v_cvt_pk_bf16_f32 v88, v82, v83
	v_cvt_pk_bf16_f32 v89, v84, v85
	v_lshl_add_u64 v[82:83], s[90:91], 0, v[220:221]
	global_store_dwordx4 v[82:83], v[86:89], off
	v_lshlrev_b32_e32 v84, 16, v88
	v_and_b32_e32 v85, 0xffff0000, v88
	v_lshlrev_b32_e32 v82, 16, v89
	v_and_b32_e32 v83, 0xffff0000, v89
	v_lshlrev_b32_e32 v88, 16, v86
	v_and_b32_e32 v89, 0xffff0000, v86
	v_lshlrev_b32_e32 v86, 16, v87
	v_and_b32_e32 v87, 0xffff0000, v87
	s_mov_b64 s[4:5], 0x58000
	s_waitcnt vmcnt(2)
; __device__ __forceinline__ unsigned cvt_pk_bf16(float lo, float hi) { unsigned r; asm volatile("v_cvt_pk_bf16_f32 %0, %1, %2" : "=v"(r) : "v"(lo), "v"(hi)); return r; }
;     __device__ __forceinline__ void operator()(const f32x4 (&acc)[2][2][4][2], const Unit& u, int wr, int wc, int fr, int fq) const {
;     ...
;                 for (int m = 0; m < 4; ++m) { const size_t off = (size_t)(row0 + ai * HALF + m * 16) * 2048 + col0 + bj * HALF;
;                     f32x4 x0 = __builtin_nontemporal_load((const f32x4*)(base + off)), x1 = __builtin_nontemporal_load((const f32x4*)(base + off + 4));
;                     if constexpr (HAS_DIN) { const u32x4 dw = __builtin_nontemporal_load((const u32x4*)(dbuf + off));
;                         x0 += (f32x4){__builtin_bit_cast(float, dw.x << 16), __builtin_bit_cast(float, dw.x & 0xffff0000u), __builtin_bit_cast(float, dw.y << 16), __builtin_bit_cast(float, dw.y & 0xffff0000u)};
;                         x1 += (f32x4){__builtin_bit_cast(float, dw.z << 16), __builtin_bit_cast(float, dw.z & 0xffff0000u), __builtin_bit_cast(float, dw.w << 16), __builtin_bit_cast(float, dw.w & 0xffff0000u)}; }
;                     f32x4 o0, o1;
;                     if constexpr (OUT_DELTA) { const f32x4 d0 = g0 * acc[ai][bj][m][0], d1 = g1 * acc[ai][bj][m][1];
;                         u32x4 w; w.x = cvt_pk_bf16(d0[0], d0[1]); w.y = cvt_pk_bf16(d0[2], d0[3]); w.z = cvt_pk_bf16(d1[0], d1[1]); w.w = cvt_pk_bf16(d1[2], d1[3]);
;                         *(u32x4*)(dbuf + off) = w;
;                         o0 = x0 + (f32x4){__builtin_bit_cast(float, w.x << 16), __builtin_bit_cast(float, w.x & 0xffff0000u), __builtin_bit_cast(float, w.y << 16), __builtin_bit_cast(float, w.y & 0xffff0000u)};
;                         o1 = x1 + (f32x4){__builtin_bit_cast(float, w.z << 16), __builtin_bit_cast(float, w.z & 0xffff0000u), __builtin_bit_cast(float, w.w << 16), __builtin_bit_cast(float, w.w & 0xffff0000u)}; }
;                     else { o0 = x0 + g0 * acc[ai][bj][m][0]; o1 = x1 + g1 * acc[ai][bj][m][1]; *(f32x4*)(out + off) = o0; *(f32x4*)(out + off + 4) = o1; }
;                     if (Hn) { const f32x4 h0 = o0 * G0, h1 = o1 * G1;
;                         u32x4 w; w.x = cvt_pk_bf16(h0[0], h0[1]); w.y = cvt_pk_bf16(h0[2], h0[3]); w.z = cvt_pk_bf16(h1[0], h1[1]); w.w = cvt_pk_bf16(h1[2], h1[3]);
;                         *(u32x4*)(Hn + off) = w;
	v_pk_add_f32 v[86:87], v[196:197], v[86:87]
	s_waitcnt vmcnt(1)
	v_pk_add_f32 v[82:83], v[214:215], v[82:83]
	v_pk_add_f32 v[88:89], v[194:195], v[88:89]
	v_pk_add_f32 v[84:85], v[212:213], v[84:85]
	v_pk_mul_f32 v[196:197], v[198:199], v[86:87]
	v_pk_mul_f32 v[194:195], v[200:201], v[88:89]
	v_pk_mul_f32 v[212:213], v[202:203], v[82:83]
	v_pk_mul_f32 v[214:215], v[204:205], v[84:85]
	v_cvt_pk_bf16_f32 v194, v194, v195
	v_cvt_pk_bf16_f32 v195, v196, v197
	s_nop 0
	v_cvt_pk_bf16_f32 v196, v214, v215
	v_cvt_pk_bf16_f32 v197, v212, v213
	v_lshl_add_u64 v[212:213], s[96:97], 0, v[220:221]
	global_store_dwordx4 v[212:213], v[194:197], off
	s_nop 1
	v_lshl_add_u64 v[196:197], v[184:185], 0, s[4:5]
	v_lshl_add_u64 v[224:225], v[196:197], 0, v[148:149]
	v_lshl_add_u64 v[194:195], v[224:225], 2, s[44:45]
	global_load_dwordx4 v[212:215], v[194:195], off nt
	global_load_dwordx4 v[220:223], v[194:195], off offset:16 nt
	v_lshlrev_b64 v[102:103], 1, v[224:225]
	v_cvt_pk_bf16_f32 v78, v78, v79
	v_cvt_pk_bf16_f32 v79, v80, v81
	v_cvt_pk_bf16_f32 v80, v74, v75
	v_cvt_pk_bf16_f32 v81, v76, v77
	v_lshl_add_u64 v[74:75], s[90:91], 0, v[102:103]
	global_store_dwordx4 v[74:75], v[78:81], off
	v_lshlrev_b32_e32 v76, 16, v80
	v_and_b32_e32 v77, 0xffff0000, v80
	v_lshlrev_b32_e32 v74, 16, v81
	v_and_b32_e32 v75, 0xffff0000, v81
	v_lshlrev_b32_e32 v80, 16, v78
	v_and_b32_e32 v81, 0xffff0000, v78
	v_lshlrev_b32_e32 v78, 16, v79
	v_and_b32_e32 v79, 0xffff0000, v79
	v_lshl_add_u64 v[102:103], s[96:97], 0, v[102:103]
	v_or_b32_e32 v148, 0x80, v148
	s_waitcnt vmcnt(2)
	v_pk_add_f32 v[78:79], v[214:215], v[78:79]
	v_pk_add_f32 v[80:81], v[212:213], v[80:81]
	s_waitcnt vmcnt(1)
	v_pk_add_f32 v[74:75], v[222:223], v[74:75]
	v_pk_add_f32 v[76:77], v[220:221], v[76:77]
	v_pk_mul_f32 v[100:101], v[198:199], v[78:79]
	v_pk_mul_f32 v[98:99], v[200:201], v[80:81]
	v_pk_mul_f32 v[104:105], v[202:203], v[74:75]
	v_pk_mul_f32 v[198:199], v[204:205], v[76:77]
	v_cvt_pk_bf16_f32 v98, v98, v99
	v_cvt_pk_bf16_f32 v99, v100, v101
	s_nop 0
	v_cvt_pk_bf16_f32 v100, v198, v199
	v_cvt_pk_bf16_f32 v101, v104, v105
	global_store_dwordx4 v[102:103], v[98:101], off
	global_load_dwordx4 v[100:103], v[178:179], off offset:512 nt
	global_load_dwordx4 v[198:201], v[178:179], off offset:528 nt
	v_lshl_add_u64 v[98:99], v[184:185], 0, v[148:149]
	v_pk_mul_f32 v[104:105], v[68:69], v[28:29]
	v_pk_mul_f32 v[68:69], v[66:67], v[26:27]
	v_cvt_pk_bf16_f32 v66, v70, v71
	v_cvt_pk_bf16_f32 v67, v72, v73
	s_nop 0
	v_cvt_pk_bf16_f32 v68, v68, v69
	v_cvt_pk_bf16_f32 v69, v104, v105
	v_lshlrev_b64 v[104:105], 1, v[98:99]
	v_lshl_add_u64 v[70:71], s[90:91], 0, v[104:105]
	global_store_dwordx4 v[70:71], v[66:69], off
	v_lshlrev_b32_e32 v72, 16, v68
	v_and_b32_e32 v73, 0xffff0000, v68
	v_lshlrev_b32_e32 v68, 16, v69
	v_and_b32_e32 v69, 0xffff0000, v69
	s_waitcnt vmcnt(1)
	v_pk_add_f32 v[70:71], v[200:201], v[68:69]
	v_lshlrev_b32_e32 v68, 16, v66
	v_and_b32_e32 v69, 0xffff0000, v66
	v_lshlrev_b32_e32 v66, 16, v67
	v_and_b32_e32 v67, 0xffff0000, v67
	v_pk_add_f32 v[98:99], v[102:103], v[66:67]
	v_pk_add_f32 v[100:101], v[100:101], v[68:69]
	v_pk_add_f32 v[72:73], v[198:199], v[72:73]
	v_pk_mul_f32 v[68:69], v[150:151], v[98:99]
	v_pk_mul_f32 v[66:67], v[152:153], v[100:101]
	v_pk_mul_f32 v[102:103], v[154:155], v[70:71]
	v_pk_mul_f32 v[178:179], v[156:157], v[72:73]
	v_cvt_pk_bf16_f32 v66, v66, v67
	v_cvt_pk_bf16_f32 v67, v68, v69
	s_nop 0
	v_cvt_pk_bf16_f32 v68, v178, v179
	v_cvt_pk_bf16_f32 v69, v102, v103
	v_lshl_add_u64 v[102:103], s[96:97], 0, v[104:105]
	global_store_dwordx4 v[102:103], v[66:69], off
	s_nop 1
	v_mul_f32_e32 v66, v101, v101
	v_mul_f32_e32 v67, v99, v99
	v_fmac_f32_e32 v66, v100, v100
	v_fmac_f32_e32 v67, v98, v98
	v_add_f32_e32 v66, v66, v67
	v_mul_f32_e32 v67, v73, v73
	v_mul_f32_e32 v68, v71, v71
	v_fmac_f32_e32 v67, v72, v72
	v_fmac_f32_e32 v68, v70, v70
	v_add_f32_e32 v67, v67, v68
	global_load_dwordx4 v[68:71], v[138:139], off offset:512 nt
	global_load_dwordx4 v[98:101], v[138:139], off offset:528 nt
	v_lshl_add_u64 v[72:73], v[140:141], 0, v[148:149]
	v_lshlrev_b64 v[72:73], 1, v[72:73]
	v_cvt_pk_bf16_f32 v62, v62, v63
	v_cvt_pk_bf16_f32 v63, v64, v65
	v_cvt_pk_bf16_f32 v64, v58, v59
	v_cvt_pk_bf16_f32 v65, v60, v61
	v_lshl_add_u64 v[58:59], s[90:91], 0, v[72:73]
	global_store_dwordx4 v[58:59], v[62:65], off
	v_lshlrev_b32_e32 v60, 16, v64
	v_and_b32_e32 v61, 0xffff0000, v64
	v_lshlrev_b32_e32 v58, 16, v65
	v_and_b32_e32 v59, 0xffff0000, v65
	v_lshlrev_b32_e32 v64, 16, v62
	v_and_b32_e32 v65, 0xffff0000, v62
	v_lshlrev_b32_e32 v62, 16, v63
	v_and_b32_e32 v63, 0xffff0000, v63
	v_lshl_add_u64 v[72:73], s[96:97], 0, v[72:73]
	v_add_f32_e32 v66, v66, v67
	v_add_f32_e32 v66, v211, v66
	s_waitcnt vmcnt(2)
	v_pk_add_f32 v[62:63], v[70:71], v[62:63]
	v_pk_add_f32 v[64:65], v[68:69], v[64:65]
	s_waitcnt vmcnt(1)
	v_pk_add_f32 v[58:59], v[100:101], v[58:59]
	v_pk_add_f32 v[60:61], v[98:99], v[60:61]
	v_pk_mul_f32 v[70:71], v[150:151], v[62:63]
	v_pk_mul_f32 v[68:69], v[152:153], v[64:65]
	v_pk_mul_f32 v[98:99], v[154:155], v[58:59]
	v_pk_mul_f32 v[100:101], v[156:157], v[60:61]
	v_cvt_pk_bf16_f32 v68, v68, v69
	v_cvt_pk_bf16_f32 v69, v70, v71
	s_nop 0
	v_cvt_pk_bf16_f32 v70, v100, v101
	v_cvt_pk_bf16_f32 v71, v98, v99
	global_store_dwordx4 v[72:73], v[68:71], off
	global_load_dwordx4 v[68:71], v[142:143], off offset:512 nt
	s_nop 0
	global_load_dwordx4 v[98:101], v[142:143], off offset:528 nt
	v_lshl_add_u64 v[72:73], v[144:145], 0, v[148:149]
	v_lshlrev_b64 v[72:73], 1, v[72:73]
	v_cvt_pk_bf16_f32 v54, v54, v55
	v_cvt_pk_bf16_f32 v55, v56, v57
	v_cvt_pk_bf16_f32 v56, v50, v51
	v_cvt_pk_bf16_f32 v57, v52, v53
	v_lshl_add_u64 v[50:51], s[90:91], 0, v[72:73]
	global_store_dwordx4 v[50:51], v[54:57], off
	v_lshlrev_b32_e32 v52, 16, v56
	v_and_b32_e32 v53, 0xffff0000, v56
	v_lshlrev_b32_e32 v50, 16, v57
	v_and_b32_e32 v51, 0xffff0000, v57
	v_lshlrev_b32_e32 v56, 16, v54
	v_and_b32_e32 v57, 0xffff0000, v54
	v_lshlrev_b32_e32 v54, 16, v55
	v_and_b32_e32 v55, 0xffff0000, v55
	v_lshl_add_u64 v[72:73], s[96:97], 0, v[72:73]
	s_waitcnt vmcnt(2)
; __device__ __forceinline__ unsigned cvt_pk_bf16(float lo, float hi) { unsigned r; asm volatile("v_cvt_pk_bf16_f32 %0, %1, %2" : "=v"(r) : "v"(lo), "v"(hi)); return r; }
;     __device__ __forceinline__ void operator()(const f32x4 (&acc)[2][2][4][2], const Unit& u, int wr, int wc, int fr, int fq) const {
;     ...
;                 for (int m = 0; m < 4; ++m) { const size_t off = (size_t)(row0 + ai * HALF + m * 16) * 2048 + col0 + bj * HALF;
;                     f32x4 x0 = __builtin_nontemporal_load((const f32x4*)(base + off)), x1 = __builtin_nontemporal_load((const f32x4*)(base + off + 4));
;                     if constexpr (HAS_DIN) { const u32x4 dw = __builtin_nontemporal_load((const u32x4*)(dbuf + off));
;                         x0 += (f32x4){__builtin_bit_cast(float, dw.x << 16), __builtin_bit_cast(float, dw.x & 0xffff0000u), __builtin_bit_cast(float, dw.y << 16), __builtin_bit_cast(float, dw.y & 0xffff0000u)};
;                         x1 += (f32x4){__builtin_bit_cast(float, dw.z << 16), __builtin_bit_cast(float, dw.z & 0xffff0000u), __builtin_bit_cast(float, dw.w << 16), __builtin_bit_cast(float, dw.w & 0xffff0000u)}; }
;                     f32x4 o0, o1;
;                     if constexpr (OUT_DELTA) { const f32x4 d0 = g0 * acc[ai][bj][m][0], d1 = g1 * acc[ai][bj][m][1];
;                         u32x4 w; w.x = cvt_pk_bf16(d0[0], d0[1]); w.y = cvt_pk_bf16(d0[2], d0[3]); w.z = cvt_pk_bf16(d1[0], d1[1]); w.w = cvt_pk_bf16(d1[2], d1[3]);
;                         *(u32x4*)(dbuf + off) = w;
;                         o0 = x0 + (f32x4){__builtin_bit_cast(float, w.x << 16), __builtin_bit_cast(float, w.x & 0xffff0000u), __builtin_bit_cast(float, w.y << 16), __builtin_bit_cast(float, w.y & 0xffff0000u)};
;                         o1 = x1 + (f32x4){__builtin_bit_cast(float, w.z << 16), __builtin_bit_cast(float, w.z & 0xffff0000u), __builtin_bit_cast(float, w.w << 16), __builtin_bit_cast(float, w.w & 0xffff0000u)}; }
;                     else { o0 = x0 + g0 * acc[ai][bj][m][0]; o1 = x1 + g1 * acc[ai][bj][m][1]; *(f32x4*)(out + off) = o0; *(f32x4*)(out + off + 4) = o1; }
;                     if (Hn) { const f32x4 h0 = o0 * G0, h1 = o1 * G1;
;                         u32x4 w; w.x = cvt_pk_bf16(h0[0], h0[1]); w.y = cvt_pk_bf16(h0[2], h0[3]); w.z = cvt_pk_bf16(h1[0], h1[1]); w.w = cvt_pk_bf16(h1[2], h1[3]);
;                         *(u32x4*)(Hn + off) = w;
	v_pk_add_f32 v[54:55], v[70:71], v[54:55]
	v_pk_add_f32 v[56:57], v[68:69], v[56:57]
	s_waitcnt vmcnt(1)
	v_pk_add_f32 v[50:51], v[100:101], v[50:51]
	v_pk_add_f32 v[52:53], v[98:99], v[52:53]
	v_pk_mul_f32 v[70:71], v[150:151], v[54:55]
	v_pk_mul_f32 v[68:69], v[152:153], v[56:57]
	v_pk_mul_f32 v[98:99], v[154:155], v[50:51]
	v_pk_mul_f32 v[100:101], v[156:157], v[52:53]
	v_cvt_pk_bf16_f32 v68, v68, v69
	v_cvt_pk_bf16_f32 v69, v70, v71
	s_nop 0
	v_cvt_pk_bf16_f32 v70, v100, v101
	v_cvt_pk_bf16_f32 v71, v98, v99
	global_store_dwordx4 v[72:73], v[68:71], off
	global_load_dwordx4 v[68:71], v[158:159], off offset:512 nt
	s_nop 0
	global_load_dwordx4 v[98:101], v[158:159], off offset:528 nt
	v_lshl_add_u64 v[72:73], v[160:161], 0, v[148:149]
	v_lshlrev_b64 v[72:73], 1, v[72:73]
	v_cvt_pk_bf16_f32 v46, v46, v47
	v_cvt_pk_bf16_f32 v47, v48, v49
	v_cvt_pk_bf16_f32 v48, v42, v43
	v_cvt_pk_bf16_f32 v49, v44, v45
	v_lshl_add_u64 v[42:43], s[90:91], 0, v[72:73]
	global_store_dwordx4 v[42:43], v[46:49], off
	v_lshlrev_b32_e32 v44, 16, v48
	v_and_b32_e32 v45, 0xffff0000, v48
	v_lshlrev_b32_e32 v42, 16, v49
	v_and_b32_e32 v43, 0xffff0000, v49
	v_lshlrev_b32_e32 v48, 16, v46
	v_and_b32_e32 v49, 0xffff0000, v46
	v_lshlrev_b32_e32 v46, 16, v47
	v_and_b32_e32 v47, 0xffff0000, v47
	v_lshl_add_u64 v[72:73], s[96:97], 0, v[72:73]
	s_waitcnt vmcnt(2)
	v_pk_add_f32 v[46:47], v[70:71], v[46:47]
	v_pk_add_f32 v[48:49], v[68:69], v[48:49]
	s_waitcnt vmcnt(1)
	v_pk_add_f32 v[42:43], v[100:101], v[42:43]
	v_pk_add_f32 v[44:45], v[98:99], v[44:45]
	v_pk_mul_f32 v[70:71], v[150:151], v[46:47]
	v_pk_mul_f32 v[68:69], v[152:153], v[48:49]
	v_pk_mul_f32 v[98:99], v[154:155], v[42:43]
	v_pk_mul_f32 v[100:101], v[156:157], v[44:45]
	v_cvt_pk_bf16_f32 v68, v68, v69
	v_cvt_pk_bf16_f32 v69, v70, v71
	s_nop 0
	v_cvt_pk_bf16_f32 v70, v100, v101
	v_cvt_pk_bf16_f32 v71, v98, v99
	global_store_dwordx4 v[72:73], v[68:71], off
	global_load_dwordx4 v[68:71], v[180:181], off offset:512 nt
	s_nop 0
	global_load_dwordx4 v[98:101], v[180:181], off offset:528 nt
	v_lshl_add_u64 v[72:73], v[182:183], 0, v[148:149]
	v_lshlrev_b64 v[72:73], 1, v[72:73]
	v_cvt_pk_bf16_f32 v38, v38, v39
	v_cvt_pk_bf16_f32 v39, v40, v41
	v_cvt_pk_bf16_f32 v40, v34, v35
	v_cvt_pk_bf16_f32 v41, v36, v37
	v_lshl_add_u64 v[34:35], s[90:91], 0, v[72:73]
	global_store_dwordx4 v[34:35], v[38:41], off
	v_lshlrev_b32_e32 v36, 16, v40
	v_and_b32_e32 v37, 0xffff0000, v40
	v_lshlrev_b32_e32 v34, 16, v41
	v_and_b32_e32 v35, 0xffff0000, v41
	v_lshlrev_b32_e32 v40, 16, v38
	v_and_b32_e32 v41, 0xffff0000, v38
	v_lshlrev_b32_e32 v38, 16, v39
	v_and_b32_e32 v39, 0xffff0000, v39
	v_lshl_add_u64 v[72:73], s[96:97], 0, v[72:73]
	s_waitcnt vmcnt(2)
	v_pk_add_f32 v[38:39], v[70:71], v[38:39]
	v_pk_add_f32 v[40:41], v[68:69], v[40:41]
	s_waitcnt vmcnt(1)
	v_pk_add_f32 v[34:35], v[100:101], v[34:35]
	v_pk_add_f32 v[36:37], v[98:99], v[36:37]
	v_pk_mul_f32 v[70:71], v[150:151], v[38:39]
	v_pk_mul_f32 v[68:69], v[152:153], v[40:41]
	v_pk_mul_f32 v[98:99], v[154:155], v[34:35]
	v_pk_mul_f32 v[100:101], v[156:157], v[36:37]
	v_cvt_pk_bf16_f32 v68, v68, v69
	v_cvt_pk_bf16_f32 v69, v70, v71
	s_nop 0
	v_cvt_pk_bf16_f32 v70, v100, v101
	v_cvt_pk_bf16_f32 v71, v98, v99
	global_store_dwordx4 v[72:73], v[68:71], off
	global_load_dwordx4 v[68:71], v[186:187], off offset:512 nt
	s_nop 0
	global_load_dwordx4 v[98:101], v[186:187], off offset:528 nt
	v_lshl_add_u64 v[72:73], v[188:189], 0, v[148:149]
	v_lshlrev_b64 v[72:73], 1, v[72:73]
	v_cvt_pk_bf16_f32 v22, v22, v23
	v_cvt_pk_bf16_f32 v23, v24, v25
	v_cvt_pk_bf16_f32 v24, v18, v19
	v_cvt_pk_bf16_f32 v25, v20, v21
	v_lshl_add_u64 v[18:19], s[90:91], 0, v[72:73]
	global_store_dwordx4 v[18:19], v[22:25], off
	v_lshlrev_b32_e32 v20, 16, v24
	v_and_b32_e32 v21, 0xffff0000, v24
	v_lshlrev_b32_e32 v18, 16, v25
	v_and_b32_e32 v19, 0xffff0000, v25
	v_lshlrev_b32_e32 v24, 16, v22
	v_and_b32_e32 v25, 0xffff0000, v22
	v_lshlrev_b32_e32 v22, 16, v23
	v_and_b32_e32 v23, 0xffff0000, v23
	v_lshl_add_u64 v[72:73], s[96:97], 0, v[72:73]
	s_waitcnt vmcnt(2)
	v_pk_add_f32 v[22:23], v[70:71], v[22:23]
	v_pk_add_f32 v[24:25], v[68:69], v[24:25]
	s_waitcnt vmcnt(1)
; __device__ __forceinline__ unsigned cvt_pk_bf16(float lo, float hi) { unsigned r; asm volatile("v_cvt_pk_bf16_f32 %0, %1, %2" : "=v"(r) : "v"(lo), "v"(hi)); return r; }
; __device__ __forceinline__ void fx_add(long long* p, float v, float scale) { atomicAdd((unsigned long long*)p, (unsigned long long)__float2ll_rn(v * scale)); }
;     __device__ __forceinline__ void operator()(const f32x4 (&acc)[2][2][4][2], const Unit& u, int wr, int wc, int fr, int fq) const {
;     ...
;                     if (Hn) { const f32x4 h0 = o0 * G0, h1 = o1 * G1;
;                         u32x4 w; w.x = cvt_pk_bf16(h0[0], h0[1]); w.y = cvt_pk_bf16(h0[2], h0[3]); w.z = cvt_pk_bf16(h1[0], h1[1]); w.w = cvt_pk_bf16(h1[2], h1[3]);
;                         *(u32x4*)(Hn + off) = w;
;                         ssq[ai][m] += ((o0[0] * o0[0] + o0[1] * o0[1]) + (o0[2] * o0[2] + o0[3] * o0[3])) + ((o1[0] * o1[0] + o1[1] * o1[1]) + (o1[2] * o1[2] + o1[3] * o1[3])); } }
;             if (bj == 0) asm volatile("" ::: "memory");
;         }
;         if (Hn) {
; #pragma unroll
;             for (int ai = 0; ai < 2; ++ai)
; #pragma unroll
;                 for (int m = 0; m < 4; ++m) { float s = ssq[ai][m]; s += __shfl_xor(s, 16); s += __shfl_xor(s, 32);
;                     if (fq == 0) fx_add(ssn + row0 + ai * HALF + m * 16, s, SS_SCALE); } }
	v_pk_add_f32 v[18:19], v[100:101], v[18:19]
	v_pk_add_f32 v[20:21], v[98:99], v[20:21]
	v_pk_mul_f32 v[70:71], v[150:151], v[22:23]
	v_pk_mul_f32 v[68:69], v[152:153], v[24:25]
	v_pk_mul_f32 v[98:99], v[154:155], v[18:19]
	v_pk_mul_f32 v[100:101], v[156:157], v[20:21]
	v_cvt_pk_bf16_f32 v68, v68, v69
	v_cvt_pk_bf16_f32 v69, v70, v71
	s_nop 0
	v_cvt_pk_bf16_f32 v70, v100, v101
	v_cvt_pk_bf16_f32 v71, v98, v99
	global_store_dwordx4 v[72:73], v[68:71], off
	global_load_dwordx4 v[68:71], v[190:191], off offset:512 nt
	s_nop 0
	global_load_dwordx4 v[98:101], v[190:191], off offset:528 nt
	v_lshl_add_u64 v[72:73], v[192:193], 0, v[148:149]
	v_lshlrev_b64 v[72:73], 1, v[72:73]
	v_cvt_pk_bf16_f32 v14, v14, v15
	v_cvt_pk_bf16_f32 v15, v16, v17
	v_cvt_pk_bf16_f32 v16, v10, v11
	v_cvt_pk_bf16_f32 v17, v12, v13
	v_lshl_add_u64 v[10:11], s[90:91], 0, v[72:73]
	global_store_dwordx4 v[10:11], v[14:17], off
	v_lshlrev_b32_e32 v12, 16, v16
	v_and_b32_e32 v13, 0xffff0000, v16
	v_lshlrev_b32_e32 v10, 16, v17
	v_and_b32_e32 v11, 0xffff0000, v17
	v_lshlrev_b32_e32 v16, 16, v14
	v_and_b32_e32 v17, 0xffff0000, v14
	v_lshlrev_b32_e32 v14, 16, v15
	v_and_b32_e32 v15, 0xffff0000, v15
	v_lshl_add_u64 v[72:73], s[96:97], 0, v[72:73]
	s_waitcnt vmcnt(2)
	v_pk_add_f32 v[14:15], v[70:71], v[14:15]
	v_pk_add_f32 v[16:17], v[68:69], v[16:17]
	s_waitcnt vmcnt(1)
	v_pk_add_f32 v[10:11], v[100:101], v[10:11]
	v_pk_add_f32 v[12:13], v[98:99], v[12:13]
	v_pk_mul_f32 v[70:71], v[150:151], v[14:15]
	v_pk_mul_f32 v[68:69], v[152:153], v[16:17]
	v_pk_mul_f32 v[98:99], v[154:155], v[10:11]
	v_pk_mul_f32 v[100:101], v[156:157], v[12:13]
	v_cvt_pk_bf16_f32 v68, v68, v69
	v_cvt_pk_bf16_f32 v69, v70, v71
	s_nop 0
	v_cvt_pk_bf16_f32 v70, v100, v101
	v_cvt_pk_bf16_f32 v71, v98, v99
	global_store_dwordx4 v[72:73], v[68:71], off
	global_load_dwordx4 v[68:71], v[194:195], off offset:512 nt
	s_nop 0
	global_load_dwordx4 v[98:101], v[194:195], off offset:528 nt
	v_lshl_add_u64 v[72:73], v[196:197], 0, v[148:149]
	v_lshlrev_b64 v[30:31], 1, v[72:73]
	v_cvt_pk_bf16_f32 v6, v6, v7
	v_cvt_pk_bf16_f32 v7, v8, v9
	v_cvt_pk_bf16_f32 v8, v2, v3
	v_cvt_pk_bf16_f32 v9, v4, v5
	v_lshl_add_u64 v[2:3], s[90:91], 0, v[30:31]
	global_store_dwordx4 v[2:3], v[6:9], off
	v_lshlrev_b32_e32 v4, 16, v8
	v_and_b32_e32 v5, 0xffff0000, v8
	v_lshlrev_b32_e32 v2, 16, v9
	v_and_b32_e32 v3, 0xffff0000, v9
	v_lshlrev_b32_e32 v8, 16, v6
	v_and_b32_e32 v9, 0xffff0000, v6
	v_lshlrev_b32_e32 v6, 16, v7
	v_and_b32_e32 v7, 0xffff0000, v7
	v_lshl_add_u64 v[30:31], s[96:97], 0, v[30:31]
	s_waitcnt vmcnt(2)
	v_pk_add_f32 v[8:9], v[68:69], v[8:9]
	v_pk_add_f32 v[6:7], v[70:71], v[6:7]
	v_pk_mul_f32 v[26:27], v[152:153], v[8:9]
	s_waitcnt vmcnt(1)
	v_pk_add_f32 v[2:3], v[100:101], v[2:3]
	v_pk_add_f32 v[4:5], v[98:99], v[4:5]
	v_pk_mul_f32 v[28:29], v[150:151], v[6:7]
	v_cvt_pk_bf16_f32 v26, v26, v27
	v_pk_mul_f32 v[32:33], v[154:155], v[2:3]
	v_cvt_pk_bf16_f32 v27, v28, v29
	v_pk_mul_f32 v[68:69], v[156:157], v[4:5]
	s_nop 0
	v_cvt_pk_bf16_f32 v28, v68, v69
	v_cvt_pk_bf16_f32 v29, v32, v33
	global_store_dwordx4 v[30:31], v[26:29], off
	s_nop 1
	v_and_b32_e32 v27, 64, v218
	v_xor_b32_e32 v26, 16, v218
	v_add_u32_e32 v27, 64, v27
	v_cmp_lt_i32_e32 vcc, v26, v27
	s_nop 1
	v_cndmask_b32_e32 v26, v218, v26, vcc
	v_lshlrev_b32_e32 v28, 2, v26
	v_xor_b32_e32 v26, 32, v218
	v_cmp_lt_i32_e32 vcc, v26, v27
	s_nop 1
	v_cndmask_b32_e32 v26, v218, v26, vcc
	v_lshlrev_b32_e32 v29, 2, v26
	ds_bpermute_b32 v26, v28, v66
	s_waitcnt lgkmcnt(0)
	v_add_f32_e32 v30, v66, v26
	ds_bpermute_b32 v31, v29, v30
	v_lshl_add_u64 v[26:27], v[146:147], 3, s[42:43]
	s_and_saveexec_b64 s[4:5], s[0:1]
	s_mov_b32 s8, 0x2f800000
	s_mov_b32 s9, 0xcf800000
	s_cbranch_execz .LBB0_558
	s_waitcnt lgkmcnt(0)
	v_add_f32_e32 v30, v30, v31
	v_mul_f32_e32 v30, 0x47800000, v30
	v_rndne_f32_e32 v30, v30
	v_mul_f32_e64 v31, |v30|, s8
	v_floor_f32_e32 v31, v31
	v_fma_f32 v32, v31, s9, |v30|
	v_cvt_u32_f32_e32 v32, v32
	v_cvt_u32_f32_e32 v31, v31
	v_ashrrev_i32_e32 v33, 31, v30
	v_xor_b32_e32 v30, v32, v33
	v_xor_b32_e32 v31, v31, v33
	v_sub_co_u32_e32 v30, vcc, v30, v33
	s_nop 1
	v_subb_co_u32_e32 v31, vcc, v31, v33, vcc
	global_atomic_add_x2 v[26:27], v[30:31], off

; #define PG8_BAR __builtin_amdgcn_s_barrier()
;     __host__ __device__ bool next(int i, Unit& u) const {
;         const long L = (long)i * G + c; if (L >= nwg) return false;
;         int wgid = (int)L; { const int q = nwg / NXCD, r = nwg % NXCD, xcd = wgid % NXCD, off = wgid / NXCD; wgid = (xcd < r ? xcd * (q + 1) : r * (q + 1) + (xcd - r) * q) + off; }
;         const int nig = WGM * nN, gid = wgid / nig, fm = gid * WGM, gsz = (nM - fm) < WGM ? (nM - fm) : WGM;
;         u.pm = fm + ((wgid % nig) % gsz); u.pn = (wgid % nig) / gsz; return true;
; template <class Epi, class Sched, bool ALIGN_EPI = false, bool SP2 = false>
; __device__ __forceinline__ void gemm_phase(PG8_LAS unsigned char* lds, const Gemm g, const Sched& S, const Epi& E) {
;     ...
;         cur = nxt; cA = nA; cB = nB; ++ui;
;         if constexpr (ALIGN_EPI) { if (wr == 1) PG8_BAR; }
.LBB0_695:
	s_and_b64 vcc, exec, s[0:1]
	s_mov_b32 s30, s27
	s_mov_b32 s29, s28
	s_mov_b64 s[6:7], s[42:43]
	s_mov_b64 s[4:5], s[52:53]
	s_cbranch_vccnz .LBB0_760
	s_cmp_eq_u32 s98, 0
	s_cbranch_scc1 .Lal_3
	s_barrier
.Lal_3:
.LBB0_696:
	s_add_i32 s26, s26, 1
	s_mul_i32 s0, s26, s77
	s_mul_hi_u32 s1, s26, s76
	s_add_i32 s1, s1, s0
	s_mul_i32 s0, s26, s76
	s_add_u32 s8, s0, s73
	s_addc_u32 s9, s1, s72
	v_cmp_gt_i64_e64 s[0:1], s[8:9], v[170:171]
	v_cmp_lt_i64_e64 s[2:3], s[8:9], v[172:173]
	s_and_b64 vcc, exec, s[0:1]
	s_cbranch_vccnz .LBB0_702
	s_ashr_i32 s9, s8, 31
	s_lshr_b32 s9, s9, 29
	s_add_i32 s10, s8, s9
	s_and_b32 s9, s10, -8
	s_sub_i32 s11, s8, s9
	s_cmp_gt_i32 s11, -1
	s_mov_b64 s[8:9], -1
	s_cbranch_scc0 .LBB0_699
	s_lshl_b32 s27, s11, 6
	s_mov_b64 s[8:9], 0

; #define PG8_STAGE(bufoff, gbase, voff) do { const char* gb_ = (const char*)(gbase); asm volatile("" : "+s"(gb_)); _Pragma("unroll") for (int _i = 0; _i < 2; ++_i) { unsigned vo_ = (voff)[_i]; asm volatile("" : "+v"(vo_));        \
;         __builtin_amdgcn_global_load_lds((const unsigned*)(gb_ + vo_), (PG8_LAS unsigned*)(lds + (bufoff) + ldsw + _i * 8192), 16, 0, 0); } } while (0)
; #define PG8_LDA(dst, b, h) do { _Pragma("unroll") for (int m = 0; m < 4; ++m) _Pragma("unroll") for (int k = 0; k < 2; ++k) dst[m][k] = *(const PG8_LAS bf16x8*)(lds + PG8_SA(b, h) + aoff + m * 2048 + k * 1024); } while (0)
; #define PG8_LDB(dst, b, h) do { _Pragma("unroll") for (int n = 0; n < 2; ++n) _Pragma("unroll") for (int k = 0; k < 2; ++k) dst[n][k] = *(const PG8_LAS bf16x8*)(lds + PG8_SB(b, h) + boff + n * 2048 + k * 1024); } while (0)
; #define PG8_MMA(ai, bj, At, Bt) do { __builtin_amdgcn_s_setprio(1); _Pragma("unroll") for (int m = 0; m < 4; ++m) _Pragma("unroll") for (int n = 0; n < 2; ++n) _Pragma("unroll") for (int k = 0; k < 2; ++k) \
;         acc[ai][bj][m][n] = __builtin_amdgcn_mfma_f32_16x16x32_bf16(Bt[n][k], At[m][k], acc[ai][bj][m][n], 0, 0, 0); __builtin_amdgcn_s_setprio(0); } while (0)
; #define PG8_WAIT_V(n) asm volatile("s_waitcnt vmcnt(" #n ")" ::: "memory")
; template <class Epi, class Sched, bool ALIGN_EPI = false, bool SP2 = false>
; __device__ __forceinline__ void gemm_phase(PG8_LAS unsigned char* lds, const Gemm g, const Sched& S, const Epi& E) {
;     ...
;             const bool last = (t == nt - 2);
;             const char* a1 = cA + (size_t)(t + 1) * kstep;
;             const char* a2 = last ? nA : cA + (size_t)(t + 2) * kstep; const char* b2 = last ? nB : cB + (size_t)(t + 2) * kstep;
;             const char* a3 = a2 + kstep; const char* b3 = b2 + kstep;
;             if (last && has_next) S.a_ready(nxt);
;             if constexpr (SP2) {
;             PG8_LDB(B0, 0, 0); PG8_LDB(B1, 0, 1); PG8_SCHED; PG8_LDA(At, 0, 0); PG8_STAGE(PG8_SA(1, 1), a1 + hstep, voffA);
;             PG8_WAIT_V(8); PG8_WAIT_L(0); PG8_BAR; PG8_MMA(0, 0, At, B0); PG8_MMA(0, 1, At, B1); PG8_BAR; PG8_SCHED;
;             PG8_LDA(At, 0, 1); PG8_STAGE(PG8_SB(0, 0), b2, voffB); PG8_STAGE(PG8_SB(0, 1), b2 + hstep, voffB); PG8_STAGE(PG8_SA(0, 0), a2, voffA);
;             PG8_WAIT_V(8); PG8_WAIT_L(0); PG8_BAR; PG8_MMA(1, 0, At, B0); PG8_MMA(1, 1, At, B1); PG8_BAR; PG8_SCHED;
.LBB0_707:
	s_add_u32 s2, s4, 0x100
	s_addc_u32 s3, s5, 0
	s_cmpk_eq_i32 s35, 0x54
	s_cselect_b32 s10, s52, s2
	s_cselect_b32 s11, s53, s3
	s_cselect_b32 s8, s42, s31
	s_cselect_b32 s9, s43, s34
	s_add_u32 s6, s10, 0x80
	s_addc_u32 s7, s11, 0
	s_add_i32 s38, 0, 0x10000
	s_add_i32 s39, 0, 0x14000
	ds_read_b128 v[34:37], v244
	ds_read_b128 v[38:41], v244 offset:1024
	ds_read_b128 v[98:101], v244 offset:2048
	ds_read_b128 v[102:105], v244 offset:3072
	ds_read_b128 v[146:149], v244 offset:16384
	ds_read_b128 v[150:153], v244 offset:17408
	ds_read_b128 v[154:157], v244 offset:18432
	ds_read_b128 v[158:161], v244 offset:19456
	s_add_u32 s4, s4, 0x160080
	s_addc_u32 s5, s5, 0
	ds_read_b128 v[178:181], v194
	ds_read_b128 v[182:185], v194 offset:1024
	ds_read_b128 v[186:189], v194 offset:2048
	ds_read_b128 v[196:199], v194 offset:3072
	ds_read_b128 v[200:203], v194 offset:4096
	ds_read_b128 v[204:207], v194 offset:5120
	ds_read_b128 v[208:211], v194 offset:6144
	ds_read_b128 v[212:215], v194 offset:7168
	s_add_i32 m0, s16, 0xc000
	s_nop 0
	global_load_lds_dwordx4 v1, s[4:5]
	s_add_i32 m0, s16, 0xe000
	s_nop 0
	global_load_lds_dwordx4 v164, s[4:5]
	s_waitcnt vmcnt(8)
	s_waitcnt lgkmcnt(0)
	s_barrier
	s_setprio 1
	s_waitcnt lgkmcnt(0)
	v_mfma_f32_16x16x32_bf16 v[142:145], v[34:37], v[178:181], v[142:145]
	v_mfma_f32_16x16x32_bf16 v[142:145], v[38:41], v[182:185], v[142:145]
	v_mfma_f32_16x16x32_bf16 v[134:137], v[34:37], v[186:189], v[134:137]
	v_mfma_f32_16x16x32_bf16 v[134:137], v[38:41], v[196:199], v[134:137]
	v_mfma_f32_16x16x32_bf16 v[126:129], v[34:37], v[200:203], v[126:129]
	v_mfma_f32_16x16x32_bf16 v[126:129], v[38:41], v[204:207], v[126:129]
	v_mfma_f32_16x16x32_bf16 v[118:121], v[34:37], v[208:211], v[118:121]
	v_mfma_f32_16x16x32_bf16 v[118:121], v[38:41], v[212:215], v[118:121]
	v_mfma_f32_16x16x32_bf16 v[138:141], v[98:101], v[178:181], v[138:141]
	v_mfma_f32_16x16x32_bf16 v[138:141], v[102:105], v[182:185], v[138:141]
	v_mfma_f32_16x16x32_bf16 v[130:133], v[98:101], v[186:189], v[130:133]
	v_mfma_f32_16x16x32_bf16 v[130:133], v[102:105], v[196:199], v[130:133]
	v_mfma_f32_16x16x32_bf16 v[122:125], v[98:101], v[200:203], v[122:125]
	v_mfma_f32_16x16x32_bf16 v[122:125], v[102:105], v[204:207], v[122:125]
	v_mfma_f32_16x16x32_bf16 v[114:117], v[98:101], v[208:211], v[114:117]
	v_mfma_f32_16x16x32_bf16 v[114:117], v[102:105], v[212:215], v[114:117]
	s_setprio 0
	s_setprio 1
	v_mfma_f32_16x16x32_bf16 v[70:73], v[146:149], v[178:181], v[70:73]
	v_mfma_f32_16x16x32_bf16 v[70:73], v[150:153], v[182:185], v[70:73]
	v_mfma_f32_16x16x32_bf16 v[62:65], v[146:149], v[186:189], v[62:65]
	v_mfma_f32_16x16x32_bf16 v[62:65], v[150:153], v[196:199], v[62:65]
	v_mfma_f32_16x16x32_bf16 v[54:57], v[146:149], v[200:203], v[54:57]
	v_mfma_f32_16x16x32_bf16 v[54:57], v[150:153], v[204:207], v[54:57]
	v_mfma_f32_16x16x32_bf16 v[46:49], v[146:149], v[208:211], v[46:49]
	v_mfma_f32_16x16x32_bf16 v[46:49], v[150:153], v[212:215], v[46:49]
	v_mfma_f32_16x16x32_bf16 v[66:69], v[154:157], v[178:181], v[66:69]
	v_mfma_f32_16x16x32_bf16 v[66:69], v[158:161], v[182:185], v[66:69]
	v_mfma_f32_16x16x32_bf16 v[58:61], v[154:157], v[186:189], v[58:61]
	v_mfma_f32_16x16x32_bf16 v[58:61], v[158:161], v[196:199], v[58:61]
	v_mfma_f32_16x16x32_bf16 v[50:53], v[154:157], v[200:203], v[50:53]
	v_mfma_f32_16x16x32_bf16 v[50:53], v[158:161], v[204:207], v[50:53]
	v_mfma_f32_16x16x32_bf16 v[42:45], v[154:157], v[208:211], v[42:45]
	v_mfma_f32_16x16x32_bf16 v[42:45], v[158:161], v[212:215], v[42:45]
	s_setprio 0
	s_barrier
	s_mov_b64 s[4:5], s[8:9]
	s_add_i32 s38, s38, s15
	ds_read_b128 v[178:181], v194 offset:16384
	ds_read_b128 v[182:185], v194 offset:17408
	ds_read_b128 v[186:189], v194 offset:18432
	ds_read_b128 v[196:199], v194 offset:19456
	ds_read_b128 v[200:203], v194 offset:20480
	ds_read_b128 v[204:207], v194 offset:21504
	ds_read_b128 v[208:211], v194 offset:22528
	ds_read_b128 v[212:215], v194 offset:23552
	s_mov_b32 m0, s38
	s_nop 0
	global_load_lds_dwordx4 v162, s[4:5]
	s_add_i32 m0, s38, 0x2000
	s_nop 0
	global_load_lds_dwordx4 v190, s[4:5]
	s_add_u32 s4, s8, 0x160000
	s_addc_u32 s5, s9, 0
	s_add_i32 s38, s39, s15
	s_mov_b32 m0, s38
	s_nop 0
	global_load_lds_dwordx4 v162, s[4:5]
	s_add_i32 m0, s38, 0x2000
	s_nop 0
	global_load_lds_dwordx4 v190, s[4:5]
	s_mov_b64 s[4:5], s[10:11]
	s_mov_b32 m0, s16
	s_nop 0
	global_load_lds_dwordx4 v1, s[4:5]
	s_mov_b32 m0, s17
	s_nop 0
	global_load_lds_dwordx4 v164, s[4:5]
	s_waitcnt vmcnt(8)
	s_waitcnt lgkmcnt(0)
	s_barrier
; #define PG8_STAGE(bufoff, gbase, voff) do { const char* gb_ = (const char*)(gbase); asm volatile("" : "+s"(gb_)); _Pragma("unroll") for (int _i = 0; _i < 2; ++_i) { unsigned vo_ = (voff)[_i]; asm volatile("" : "+v"(vo_));        \
;         __builtin_amdgcn_global_load_lds((const unsigned*)(gb_ + vo_), (PG8_LAS unsigned*)(lds + (bufoff) + ldsw + _i * 8192), 16, 0, 0); } } while (0)
; #define PG8_LDA(dst, b, h) do { _Pragma("unroll") for (int m = 0; m < 4; ++m) _Pragma("unroll") for (int k = 0; k < 2; ++k) dst[m][k] = *(const PG8_LAS bf16x8*)(lds + PG8_SA(b, h) + aoff + m * 2048 + k * 1024); } while (0)
; #define PG8_LDB(dst, b, h) do { _Pragma("unroll") for (int n = 0; n < 2; ++n) _Pragma("unroll") for (int k = 0; k < 2; ++k) dst[n][k] = *(const PG8_LAS bf16x8*)(lds + PG8_SB(b, h) + boff + n * 2048 + k * 1024); } while (0)
; #define PG8_MMA(ai, bj, At, Bt) do { __builtin_amdgcn_s_setprio(1); _Pragma("unroll") for (int m = 0; m < 4; ++m) _Pragma("unroll") for (int n = 0; n < 2; ++n) _Pragma("unroll") for (int k = 0; k < 2; ++k) \
;         acc[ai][bj][m][n] = __builtin_amdgcn_mfma_f32_16x16x32_bf16(Bt[n][k], At[m][k], acc[ai][bj][m][n], 0, 0, 0); __builtin_amdgcn_s_setprio(0); } while (0)
; #define PG8_WAIT_V(n) asm volatile("s_waitcnt vmcnt(" #n ")" ::: "memory")
; #define PG8_WAIT_L(n) asm volatile("s_waitcnt lgkmcnt(" #n ")" ::: "memory")
; #define PG8_BAR __builtin_amdgcn_s_barrier()
; #define PG8_SCHED __builtin_amdgcn_sched_barrier(0)
; template <class Epi, class Sched, bool ALIGN_EPI = false, bool SP2 = false>
; __device__ __forceinline__ void gemm_phase(PG8_LAS unsigned char* lds, const Gemm g, const Sched& S, const Epi& E) {
;     ...
;             PG8_WAIT_V(8); PG8_WAIT_L(0); PG8_BAR; PG8_MMA(1, 0, At, B0); PG8_MMA(1, 1, At, B1); PG8_BAR; PG8_SCHED;
;             PG8_LDB(B0, 1, 0); PG8_LDB(B1, 1, 1); PG8_SCHED; PG8_LDA(At, 1, 0); PG8_STAGE(PG8_SA(0, 1), a2 + hstep, voffA);
;             PG8_WAIT_V(8); PG8_WAIT_L(0); PG8_BAR; PG8_MMA(0, 0, At, B0); PG8_MMA(0, 1, At, B1); PG8_BAR; PG8_SCHED;
	s_setprio 1
	s_waitcnt lgkmcnt(0)
	v_mfma_f32_16x16x32_bf16 v[110:113], v[34:37], v[178:181], v[110:113]
	v_mfma_f32_16x16x32_bf16 v[110:113], v[38:41], v[182:185], v[110:113]
	v_mfma_f32_16x16x32_bf16 v[94:97], v[34:37], v[186:189], v[94:97]
	v_mfma_f32_16x16x32_bf16 v[94:97], v[38:41], v[196:199], v[94:97]
	v_mfma_f32_16x16x32_bf16 v[86:89], v[34:37], v[200:203], v[86:89]
	v_mfma_f32_16x16x32_bf16 v[86:89], v[38:41], v[204:207], v[86:89]
	v_mfma_f32_16x16x32_bf16 v[34:37], v[34:37], v[208:211], v[78:81]
	v_mfma_f32_16x16x32_bf16 v[34:37], v[38:41], v[212:215], v[34:37]
	v_mfma_f32_16x16x32_bf16 v[106:109], v[98:101], v[178:181], v[106:109]
	v_mfma_f32_16x16x32_bf16 v[106:109], v[102:105], v[182:185], v[106:109]
	v_mfma_f32_16x16x32_bf16 v[90:93], v[98:101], v[186:189], v[90:93]
	v_mfma_f32_16x16x32_bf16 v[90:93], v[102:105], v[196:199], v[90:93]
	v_mfma_f32_16x16x32_bf16 v[82:85], v[98:101], v[200:203], v[82:85]
	v_mfma_f32_16x16x32_bf16 v[82:85], v[102:105], v[204:207], v[82:85]
	v_mfma_f32_16x16x32_bf16 v[38:41], v[98:101], v[208:211], v[74:77]
	v_mfma_f32_16x16x32_bf16 v[38:41], v[102:105], v[212:215], v[38:41]
	s_setprio 0
	s_setprio 1
	v_mfma_f32_16x16x32_bf16 v[30:33], v[146:149], v[178:181], v[30:33]
	v_mfma_f32_16x16x32_bf16 v[30:33], v[150:153], v[182:185], v[30:33]
	v_mfma_f32_16x16x32_bf16 v[22:25], v[146:149], v[186:189], v[22:25]
	v_mfma_f32_16x16x32_bf16 v[22:25], v[150:153], v[196:199], v[22:25]
	v_mfma_f32_16x16x32_bf16 v[14:17], v[146:149], v[200:203], v[14:17]
	v_mfma_f32_16x16x32_bf16 v[14:17], v[150:153], v[204:207], v[14:17]
	v_mfma_f32_16x16x32_bf16 v[6:9], v[146:149], v[208:211], v[6:9]
	v_mfma_f32_16x16x32_bf16 v[6:9], v[150:153], v[212:215], v[6:9]
	v_mfma_f32_16x16x32_bf16 v[26:29], v[154:157], v[178:181], v[26:29]
	v_mfma_f32_16x16x32_bf16 v[26:29], v[158:161], v[182:185], v[26:29]
	v_mfma_f32_16x16x32_bf16 v[18:21], v[154:157], v[186:189], v[18:21]
	v_mfma_f32_16x16x32_bf16 v[18:21], v[158:161], v[196:199], v[18:21]
	v_mfma_f32_16x16x32_bf16 v[10:13], v[154:157], v[200:203], v[10:13]
	v_mfma_f32_16x16x32_bf16 v[10:13], v[158:161], v[204:207], v[10:13]
	v_mfma_f32_16x16x32_bf16 v[2:5], v[154:157], v[208:211], v[2:5]
	v_mfma_f32_16x16x32_bf16 v[2:5], v[158:161], v[212:215], v[2:5]
	s_setprio 0
	s_barrier
	s_add_i32 s38, 0, 0x18000
	s_add_i32 s39, 0, 0x1c000
	ds_read_b128 v[74:77], v244 offset:32768
	ds_read_b128 v[78:81], v244 offset:33792
	ds_read_b128 v[98:101], v244 offset:34816
	ds_read_b128 v[102:105], v244 offset:35840
	ds_read_b128 v[146:149], v244 offset:49152
	ds_read_b128 v[150:153], v244 offset:50176
	ds_read_b128 v[154:157], v244 offset:51200
	ds_read_b128 v[158:161], v244 offset:52224
	s_add_u32 s4, s10, 0x160000
	s_addc_u32 s5, s11, 0
	s_mov_b32 m0, s18
	ds_read_b128 v[178:181], v194 offset:32768
	ds_read_b128 v[182:185], v194 offset:33792
	ds_read_b128 v[186:189], v194 offset:34816
	ds_read_b128 v[196:199], v194 offset:35840
	ds_read_b128 v[200:203], v194 offset:36864
	ds_read_b128 v[204:207], v194 offset:37888
	ds_read_b128 v[208:211], v194 offset:38912
	ds_read_b128 v[212:215], v194 offset:39936
	s_nop 0
	global_load_lds_dwordx4 v1, s[4:5]
	s_mov_b32 m0, s19
	s_nop 0
	global_load_lds_dwordx4 v164, s[4:5]
	s_waitcnt vmcnt(8)
	s_waitcnt lgkmcnt(0)
	s_barrier
	s_setprio 1
	s_waitcnt lgkmcnt(0)
	v_mfma_f32_16x16x32_bf16 v[142:145], v[74:77], v[178:181], v[142:145]
	v_mfma_f32_16x16x32_bf16 v[142:145], v[78:81], v[182:185], v[142:145]
	v_mfma_f32_16x16x32_bf16 v[134:137], v[74:77], v[186:189], v[134:137]
	v_mfma_f32_16x16x32_bf16 v[134:137], v[78:81], v[196:199], v[134:137]
	v_mfma_f32_16x16x32_bf16 v[126:129], v[74:77], v[200:203], v[126:129]
	v_mfma_f32_16x16x32_bf16 v[126:129], v[78:81], v[204:207], v[126:129]
	v_mfma_f32_16x16x32_bf16 v[118:121], v[74:77], v[208:211], v[118:121]
	v_mfma_f32_16x16x32_bf16 v[118:121], v[78:81], v[212:215], v[118:121]
	v_mfma_f32_16x16x32_bf16 v[138:141], v[98:101], v[178:181], v[138:141]
	v_mfma_f32_16x16x32_bf16 v[138:141], v[102:105], v[182:185], v[138:141]
	v_mfma_f32_16x16x32_bf16 v[130:133], v[98:101], v[186:189], v[130:133]
	v_mfma_f32_16x16x32_bf16 v[130:133], v[102:105], v[196:199], v[130:133]
	v_mfma_f32_16x16x32_bf16 v[122:125], v[98:101], v[200:203], v[122:125]
	v_mfma_f32_16x16x32_bf16 v[122:125], v[102:105], v[204:207], v[122:125]
	v_mfma_f32_16x16x32_bf16 v[114:117], v[98:101], v[208:211], v[114:117]
	v_mfma_f32_16x16x32_bf16 v[114:117], v[102:105], v[212:215], v[114:117]
	s_setprio 0
	s_setprio 1
	v_mfma_f32_16x16x32_bf16 v[70:73], v[146:149], v[178:181], v[70:73]
	v_mfma_f32_16x16x32_bf16 v[70:73], v[150:153], v[182:185], v[70:73]
	v_mfma_f32_16x16x32_bf16 v[62:65], v[146:149], v[186:189], v[62:65]
	v_mfma_f32_16x16x32_bf16 v[62:65], v[150:153], v[196:199], v[62:65]
	v_mfma_f32_16x16x32_bf16 v[54:57], v[146:149], v[200:203], v[54:57]
	v_mfma_f32_16x16x32_bf16 v[54:57], v[150:153], v[204:207], v[54:57]
	v_mfma_f32_16x16x32_bf16 v[46:49], v[146:149], v[208:211], v[46:49]
	v_mfma_f32_16x16x32_bf16 v[46:49], v[150:153], v[212:215], v[46:49]
	v_mfma_f32_16x16x32_bf16 v[66:69], v[154:157], v[178:181], v[66:69]
	v_mfma_f32_16x16x32_bf16 v[66:69], v[158:161], v[182:185], v[66:69]
	v_mfma_f32_16x16x32_bf16 v[58:61], v[154:157], v[186:189], v[58:61]
	v_mfma_f32_16x16x32_bf16 v[58:61], v[158:161], v[196:199], v[58:61]
	v_mfma_f32_16x16x32_bf16 v[50:53], v[154:157], v[200:203], v[50:53]
	v_mfma_f32_16x16x32_bf16 v[50:53], v[158:161], v[204:207], v[50:53]
	v_mfma_f32_16x16x32_bf16 v[42:45], v[154:157], v[208:211], v[42:45]
	v_mfma_f32_16x16x32_bf16 v[42:45], v[158:161], v[212:215], v[42:45]
	s_setprio 0
	s_barrier
; #define PG8_STAGE(bufoff, gbase, voff) do { const char* gb_ = (const char*)(gbase); asm volatile("" : "+s"(gb_)); _Pragma("unroll") for (int _i = 0; _i < 2; ++_i) { unsigned vo_ = (voff)[_i]; asm volatile("" : "+v"(vo_));        \
;         __builtin_amdgcn_global_load_lds((const unsigned*)(gb_ + vo_), (PG8_LAS unsigned*)(lds + (bufoff) + ldsw + _i * 8192), 16, 0, 0); } } while (0)
; #define PG8_LDA(dst, b, h) do { _Pragma("unroll") for (int m = 0; m < 4; ++m) _Pragma("unroll") for (int k = 0; k < 2; ++k) dst[m][k] = *(const PG8_LAS bf16x8*)(lds + PG8_SA(b, h) + aoff + m * 2048 + k * 1024); } while (0)
; #define PG8_WAIT_V(n) asm volatile("s_waitcnt vmcnt(" #n ")" ::: "memory")
; #define PG8_WAIT_L(n) asm volatile("s_waitcnt lgkmcnt(" #n ")" ::: "memory")
; #define PG8_BAR __builtin_amdgcn_s_barrier()
; #define PG8_SCHED __builtin_amdgcn_sched_barrier(0)
;     __device__ __forceinline__ void operator()(const f32x4 (&acc)[2][2][4][2], const Unit& u, int wr, int wc, int fr, int fq) const {
;         const int row0 = u.pm * BM + wr * 64 + fr, col0 = u.pn * BM + wc * 32 + 8 * fq, b = (u.pm * BM) / rows_per_batch;
;         const float* g = gate + (size_t)b * gate_bstride + col0;
;         float ssq[2][4];
; #pragma unroll
;         for (int ai = 0; ai < 2; ++ai)
; #pragma unroll
;             for (int m = 0; m < 4; ++m) ssq[ai][m] = 0.f;
;         f32x4 gv[2][2], Gv[2][2];
; #pragma unroll
;         for (int bj = 0; bj < 2; ++bj) { gv[bj][0] = *(const f32x4*)(g + bj * HALF); gv[bj][1] = *(const f32x4*)(g + bj * HALF + 4); Gv[bj][0] = (f32x4){0.f, 0.f, 0.f, 0.f}; Gv[bj][1] = (f32x4){0.f, 0.f, 0.f, 0.f};
;             if (Hn) { const float* sc = scnext + (size_t)b * gate_bstride + col0 + bj * HALF;
;                 Gv[bj][0] = *(const f32x4*)(gnext + col0 + bj * HALF) * (1.0f + *(const f32x4*)(sc)); Gv[bj][1] = *(const f32x4*)(gnext + col0 + bj * HALF + 4) * (1.0f + *(const f32x4*)(sc + 4)); } }
; template <class Epi, class Sched, bool ALIGN_EPI = false, bool SP2 = false>
; __device__ __forceinline__ void gemm_phase(PG8_LAS unsigned char* lds, const Gemm g, const Sched& S, const Epi& E) {
;     ...
;             PG8_LDA(At, 1, 1); PG8_STAGE(PG8_SB(1, 0), b3, voffB); PG8_STAGE(PG8_SB(1, 1), b3 + hstep, voffB); PG8_STAGE(PG8_SA(1, 0), a3, voffA);
;             PG8_WAIT_V(8); PG8_WAIT_L(0); PG8_BAR; PG8_MMA(1, 0, At, B0); PG8_MMA(1, 1, At, B1); PG8_BAR; PG8_SCHED;
	s_add_u32 s4, s8, 0x80
	s_addc_u32 s5, s9, 0
	s_add_i32 s10, s38, s15
	ds_read_b128 v[178:181], v194 offset:49152
	ds_read_b128 v[182:185], v194 offset:50176
	ds_read_b128 v[186:189], v194 offset:51200
	ds_read_b128 v[196:199], v194 offset:52224
	ds_read_b128 v[200:203], v194 offset:53248
	ds_read_b128 v[204:207], v194 offset:54272
	ds_read_b128 v[208:211], v194 offset:55296
	ds_read_b128 v[212:215], v194 offset:56320
	s_mov_b32 m0, s10
	s_nop 0
	global_load_lds_dwordx4 v162, s[4:5]
	s_add_i32 m0, s10, 0x2000
	s_nop 0
	global_load_lds_dwordx4 v190, s[4:5]
	s_add_u32 s4, s8, 0x160080
	s_addc_u32 s5, s9, 0
	s_add_i32 s8, s39, s15
	s_mov_b32 m0, s8
	s_nop 0
	global_load_lds_dwordx4 v162, s[4:5]
	s_add_i32 m0, s8, 0x2000
	s_nop 0
	global_load_lds_dwordx4 v190, s[4:5]
	s_mov_b32 m0, s24
	s_nop 0
	global_load_lds_dwordx4 v1, s[6:7]
	s_mov_b32 m0, s25
	s_nop 0
	global_load_lds_dwordx4 v164, s[6:7]
	s_waitcnt vmcnt(8)
	s_waitcnt lgkmcnt(0)
	s_barrier
	s_setprio 1
	s_waitcnt lgkmcnt(0)
	v_mfma_f32_16x16x32_bf16 v[110:113], v[74:77], v[178:181], v[110:113]
	v_mfma_f32_16x16x32_bf16 v[110:113], v[78:81], v[182:185], v[110:113]
	v_mfma_f32_16x16x32_bf16 v[94:97], v[74:77], v[186:189], v[94:97]
	v_mfma_f32_16x16x32_bf16 v[94:97], v[78:81], v[196:199], v[94:97]
	v_mfma_f32_16x16x32_bf16 v[86:89], v[74:77], v[200:203], v[86:89]
	v_mfma_f32_16x16x32_bf16 v[86:89], v[78:81], v[204:207], v[86:89]
	v_mfma_f32_16x16x32_bf16 v[34:37], v[74:77], v[208:211], v[34:37]
	v_mfma_f32_16x16x32_bf16 v[78:81], v[78:81], v[212:215], v[34:37]
	v_mfma_f32_16x16x32_bf16 v[106:109], v[98:101], v[178:181], v[106:109]
	v_mfma_f32_16x16x32_bf16 v[106:109], v[102:105], v[182:185], v[106:109]
	v_mfma_f32_16x16x32_bf16 v[90:93], v[98:101], v[186:189], v[90:93]
	v_mfma_f32_16x16x32_bf16 v[90:93], v[102:105], v[196:199], v[90:93]
	v_mfma_f32_16x16x32_bf16 v[82:85], v[98:101], v[200:203], v[82:85]
	v_mfma_f32_16x16x32_bf16 v[82:85], v[102:105], v[204:207], v[82:85]
	v_mfma_f32_16x16x32_bf16 v[34:37], v[98:101], v[208:211], v[38:41]
	v_mfma_f32_16x16x32_bf16 v[74:77], v[102:105], v[212:215], v[34:37]
	s_setprio 0
	s_setprio 1
	v_mfma_f32_16x16x32_bf16 v[30:33], v[146:149], v[178:181], v[30:33]
	v_mfma_f32_16x16x32_bf16 v[30:33], v[150:153], v[182:185], v[30:33]
	v_mfma_f32_16x16x32_bf16 v[22:25], v[146:149], v[186:189], v[22:25]
	v_mfma_f32_16x16x32_bf16 v[22:25], v[150:153], v[196:199], v[22:25]
	v_mfma_f32_16x16x32_bf16 v[14:17], v[146:149], v[200:203], v[14:17]
	v_mfma_f32_16x16x32_bf16 v[14:17], v[150:153], v[204:207], v[14:17]
	v_mfma_f32_16x16x32_bf16 v[6:9], v[146:149], v[208:211], v[6:9]
	v_mfma_f32_16x16x32_bf16 v[6:9], v[150:153], v[212:215], v[6:9]
	v_mfma_f32_16x16x32_bf16 v[26:29], v[154:157], v[178:181], v[26:29]
	v_mfma_f32_16x16x32_bf16 v[26:29], v[158:161], v[182:185], v[26:29]
	v_mfma_f32_16x16x32_bf16 v[18:21], v[154:157], v[186:189], v[18:21]
	v_mfma_f32_16x16x32_bf16 v[18:21], v[158:161], v[196:199], v[18:21]
	v_mfma_f32_16x16x32_bf16 v[10:13], v[154:157], v[200:203], v[10:13]
	v_mfma_f32_16x16x32_bf16 v[10:13], v[158:161], v[204:207], v[10:13]
	v_mfma_f32_16x16x32_bf16 v[2:5], v[154:157], v[208:211], v[2:5]
	v_mfma_f32_16x16x32_bf16 v[2:5], v[158:161], v[212:215], v[2:5]
	s_setprio 0
	s_barrier
	s_add_i32 s35, s35, 2
	s_add_u32 s31, s31, 0x100
	s_addc_u32 s34, s34, 0
	s_cmpk_gt_u32 s35, 0x55
	s_mov_b64 s[4:5], s[2:3]
	s_cbranch_scc0 .LBB0_707
	s_cmp_lg_u32 s98, 0
	s_cbranch_scc1 .Lal_4
	s_barrier
.Lal_4:
	s_ashr_i32 s2, s29, 31
	s_lshr_b32 s2, s2, 27
	s_add_i32 s2, s29, s2
	s_ashr_i32 s2, s2, 5
	v_lshl_or_b32 v156, s30, 8, v193
	s_mul_i32 s5, s2, 0xc000
	v_ashrrev_i32_e32 v157, 31, v156
	s_mul_hi_i32 s4, s2, 0xc000
	s_add_u32 s2, s20, s5
	s_addc_u32 s3, s21, s4
	v_lshlrev_b64 v[34:35], 2, v[156:157]
	v_lshl_add_u64 v[38:39], s[2:3], 0, v[34:35]
	global_load_dwordx4 v[98:101], v[38:39], off offset:16
	global_load_dwordx4 v[102:105], v[38:39], off
	s_add_u32 s2, s22, s5
	s_addc_u32 s3, s23, s4
	v_lshl_add_u64 v[148:149], s[2:3], 0, v[34:35]
	v_lshl_add_u64 v[146:147], s[48:49], 0, v[34:35]
	v_mov_b32_e32 v158, 0
	v_cndmask_b32_e64 v34, 0, 1, s[46:47]
	v_cmp_ne_u32_e64 s[2:3], 1, v34
	s_andn2_b64 vcc, exec, s[46:47]
	v_mov_b32_e32 v159, v158
	v_mov_b32_e32 v160, v158
	v_mov_b32_e32 v161, v158
	v_mov_b32_e32 v178, v158
	v_mov_b32_e32 v179, v158
	v_mov_b32_e32 v180, v158
	v_mov_b32_e32 v181, v158
	s_cbranch_vccnz .LBB0_710
	global_load_dwordx4 v[34:37], v[148:149], off
	global_load_dwordx4 v[150:153], v[148:149], off offset:16
	global_load_dwordx4 v[158:161], v[146:147], off
	global_load_dwordx4 v[178:181], v[146:147], off offset:16
	s_waitcnt vmcnt(0)
	v_pk_add_f32 v[36:37], v[36:37], 1.0 op_sel_hi:[1,0]
	v_pk_add_f32 v[34:35], v[34:35], 1.0 op_sel_hi:[1,0]
	v_pk_add_f32 v[40:41], v[152:153], 1.0 op_sel_hi:[1,0]
	v_pk_add_f32 v[150:151], v[150:151], 1.0 op_sel_hi:[1,0]
	v_pk_mul_f32 v[160:161], v[160:161], v[36:37]
	v_pk_mul_f32 v[158:159], v[158:159], v[34:35]
	v_pk_mul_f32 v[180:181], v[180:181], v[40:41]
	v_pk_mul_f32 v[178:179], v[178:179], v[150:151]
